# hand-written software-pipelined residual+LayerNorm phase (2 rows in flight per wave, counted vmcnt), folded modulation constants
# speedup vs baseline: 1.0139x; 1.0139x over previous
; __device__ __forceinline__ int fresh_tid(int wid) { return wid * 64 + fresh_lane(); }
; __device__ void phase_resid_ln(PP P, int wid, int layer, int sub, const bf16_t* usrc, const bf16_t* msrc, bf16_t* Adst) {
;     const int tidx = fresh_tid(wid);
;     const float* mod = (const float*)(P->ws + WS_MOD);
;     const int wv = tidx >> 6, lane = tidx & 63;
;     const float* lng = P->in[sub == 0 ? 6 : 8] + layer * D, *lnb = P->in[sub == 0 ? 7 : 9] + layer * D;
;     const int nl = sub == 0 ? layer : layer + 1, nsub = sub == 0 ? 1 : 0;
;     const bool has_next = nl < DEPTH, xlayout = has_next && nsub == 0 && (nl & 1), x_from_input = layer == 0 && sub == 0;
;     const bool src_xlayout = sub == 0 && (layer & 1);
;     const int rpw = (MT + (int)gridDim.x - 1) / (int)gridDim.x, rbeg = blockIdx.x * rpw, rend = (rbeg + rpw) < MT ? (rbeg + rpw) : MT;
;     ...
;         const int row2 = row + 8;
;         const int nr = (row2 < rend && (row2 >> 11) == seq) ? 2 : 1;
;         float y[2][16], sum[2] = {0.f, 0.f}, sq[2] = {0.f, 0.f};
; #pragma unroll
;         for (int rr = 0; rr < 2; ++rr) {
;             if (rr < nr) {
;                 const int r = row + rr * 8;
; #pragma unroll
;                 for (int h = 0; h < 2; ++h) {
;                     const int c8 = h * 512 + lane * 8; float x[8], m[8];
;                     if (x_from_input) load8f(xin_row(P, r) + c8, x);
;                     else { float u[8]; load_A(usrc, src_xlayout, r, c8, u);
; #pragma unroll
;                         for (int e = 0; e < 8; ++e) x[e] = (u[e] - sh[h * 8 + e]) * sc[h * 8 + e]; }
;                     unpack8(*(const u32x4*)(msrc + (size_t)r * D + c8), m);
; #pragma unroll
;                     for (int e = 0; e < 8; ++e) { const float v = ALPHA * x[e] + gt[h * 8 + e] * m[e]; y[rr][h * 8 + e] = v; sum[rr] += v; sq[rr] += v * v; }
.LBB0_238:
	s_andn2_b64 vcc, exec, s[4:5]
	s_cbranch_vccnz .LBB0_306
	v_mbcnt_lo_u32_b32 v0, -1, 0
	v_mbcnt_hi_u32_b32 v0, -1, v0
	v_readlane_b32 s4, v255, 18
	v_readlane_b32 s5, v255, 2
	s_mov_b32 s72, s1
	s_mov_b64 s[76:77], s[12:13]
	s_lshr_b32 s5, s5, 6
	s_add_i32 s64, s4, s5
	s_add_u32 s70, s22, 0xe200000
	s_addc_u32 s71, s23, 0
	s_mov_b32 s65, -1
	s_mov_b32 s75, 0xffff0000
	s_lshl_b32 s4, s72, 4
	s_add_u32 s6, s58, s4
	s_addc_u32 s7, s59, 0
	s_load_dwordx4 s[80:83], s[6:7], 0x30
	s_load_dwordx4 s[84:87], s[58:59], 0x0
	v_lshlrev_b32_e32 v1, 4, v0
	v_lshlrev_b32_e32 v6, 5, v0
	v_lshrrev_b32_e32 v7, 1, v0
	v_mul_u32_u24_e32 v7, 0x3c0000, v7
	v_and_b32_e32 v2, 1, v0
	v_lshl_add_u32 v7, v2, 4, v7
	s_and_b32 s4, s25, 1
	s_xor_b32 s5, s72, 1
	s_and_b32 s73, s4, s5
	s_xor_b32 s4, s4, 1
	s_and_b32 s74, s4, s72
	s_cmp_lg_u32 s73, 0
	s_cselect_b64 vcc, -1, 0
	v_add_u32_e32 v3, 0x400, v1
	v_add_u32_e32 v5, 0x7800000, v7
	v_cndmask_b32_e32 v2, v1, v7, vcc
	v_cndmask_b32_e32 v3, v3, v5, vcc
	s_cmp_lg_u32 s74, 0
	s_cselect_b64 vcc, -1, 0
	v_add_u32_e32 v4, 0x400, v1
	s_nop 1
	v_cndmask_b32_e32 v5, v4, v5, vcc
	v_cndmask_b32_e32 v4, v1, v7, vcc
	s_waitcnt lgkmcnt(0)
	s_lshl_b32 s4, s25, 12
	s_add_u32 s80, s80, s4
	s_addc_u32 s81, s81, 0
	s_add_u32 s82, s82, s4
	s_addc_u32 s83, s83, 0
	s_or_b32 s4, s25, s72
	s_cmp_eq_u32 s4, 0
	s_cbranch_scc1 .Lrl_X_start
	s_add_i32 s4, s25, s72
	s_cmp_eq_u32 s4, 4
	s_cbranch_scc0 .Lrl_N_start
	s_load_dwordx2 s[84:85], s[58:59], 0xd8
	s_waitcnt lgkmcnt(0)
	s_branch .Lrl_F_start
.Lrl_N_start:
	s_lshl_b32 s4, s64, 11
	s_lshr_b32 s5, s64, 5
	s_mul_i32 s5, s5, 0x600
	s_and_b32 s6, s64, 31
	s_lshl_b32 s6, s6, 5
	s_add_i32 s5, s5, s6
	s_cmp_lg_u32 s73, 0
	s_cselect_b32 s5, s5, s4
	s_add_u32 s68, s60, s5
	s_addc_u32 s69, s61, 0
	s_add_u32 s66, s76, s4
	s_addc_u32 s67, s77, 0
	global_load_dwordx4 v[88:91], v2, s[68:69]
	global_load_dwordx4 v[92:95], v3, s[68:69]
	global_load_dwordx4 v[104:107], v1, s[66:67]
	global_load_dwordx4 v[108:111], v1, s[66:67] offset:1024
	s_add_i32 s88, s64, 8
	s_cmp_lt_u32 s88, s46
	s_cselect_b32 s89, s88, s64
	s_lshl_b32 s4, s89, 11
	s_lshr_b32 s5, s89, 5
	s_mul_i32 s5, s5, 0x600
	s_and_b32 s6, s89, 31
	s_lshl_b32 s6, s6, 5
	s_add_i32 s5, s5, s6
	s_cmp_lg_u32 s73, 0
	s_cselect_b32 s5, s5, s4
	s_add_u32 s68, s60, s5
	s_addc_u32 s69, s61, 0
	s_add_u32 s66, s76, s4
	s_addc_u32 s67, s77, 0
	global_load_dwordx4 v[112:115], v2, s[68:69]
	global_load_dwordx4 v[116:119], v3, s[68:69]
	global_load_dwordx4 v[128:131], v1, s[66:67]
	global_load_dwordx4 v[132:135], v1, s[66:67] offset:1024
.Lrl_N_loop:
	s_lshr_b32 s4, s64, 11
	s_cmp_eq_u32 s4, s65
	s_cbranch_scc1 .Lrl_N_okA
	s_mov_b32 s91, 0
	s_branch .Lrl_par_N
.Lrl_N_okA:
	s_waitcnt vmcnt(8)
	v_lshlrev_b32_e32 v168, 16, v88
	v_and_b32_e32 v169, s75, v88
	v_lshlrev_b32_e32 v170, 16, v89
	v_and_b32_e32 v171, s75, v89
	v_lshlrev_b32_e32 v172, 16, v90
	v_and_b32_e32 v173, s75, v90
	v_lshlrev_b32_e32 v174, 16, v91
	v_and_b32_e32 v175, s75, v91
	v_lshlrev_b32_e32 v176, 16, v92
	v_and_b32_e32 v177, s75, v92
	v_lshlrev_b32_e32 v178, 16, v93
	v_and_b32_e32 v179, s75, v93
	v_lshlrev_b32_e32 v180, 16, v94
	v_and_b32_e32 v181, s75, v94
	v_lshlrev_b32_e32 v182, 16, v95
	v_and_b32_e32 v183, s75, v95
	v_pk_fma_f32 v[136:137], v[168:169], v[24:25], v[40:41]
	v_pk_fma_f32 v[138:139], v[170:171], v[26:27], v[42:43]
	v_pk_fma_f32 v[140:141], v[172:173], v[28:29], v[44:45]
	v_pk_fma_f32 v[142:143], v[174:175], v[30:31], v[46:47]
	v_pk_fma_f32 v[144:145], v[176:177], v[32:33], v[48:49]
	v_pk_fma_f32 v[146:147], v[178:179], v[34:35], v[50:51]
	v_pk_fma_f32 v[148:149], v[180:181], v[36:37], v[52:53]
	v_pk_fma_f32 v[150:151], v[182:183], v[38:39], v[54:55]
	v_lshlrev_b32_e32 v168, 16, v104
	v_and_b32_e32 v169, s75, v104
	v_lshlrev_b32_e32 v170, 16, v105
	v_and_b32_e32 v171, s75, v105
	v_lshlrev_b32_e32 v172, 16, v106
	v_and_b32_e32 v173, s75, v106
	v_lshlrev_b32_e32 v174, 16, v107
	v_and_b32_e32 v175, s75, v107
	v_lshlrev_b32_e32 v176, 16, v108
	v_and_b32_e32 v177, s75, v108
	v_lshlrev_b32_e32 v178, 16, v109
	v_and_b32_e32 v179, s75, v109
	v_lshlrev_b32_e32 v180, 16, v110
	v_and_b32_e32 v181, s75, v110
	v_lshlrev_b32_e32 v182, 16, v111
	v_and_b32_e32 v183, s75, v111
	s_add_i32 s89, s64, 16
	s_cmp_lt_u32 s89, s46
	s_cselect_b32 s89, s89, s64
	s_lshl_b32 s4, s89, 11
	s_lshr_b32 s5, s89, 5
	s_mul_i32 s5, s5, 0x600
	s_and_b32 s6, s89, 31
	s_lshl_b32 s6, s6, 5
	s_add_i32 s5, s5, s6
	s_cmp_lg_u32 s73, 0
	s_cselect_b32 s5, s5, s4
	s_add_u32 s68, s60, s5
	s_addc_u32 s69, s61, 0
	s_add_u32 s66, s76, s4
	s_addc_u32 s67, s77, 0
	global_load_dwordx4 v[88:91], v2, s[68:69]
	global_load_dwordx4 v[92:95], v3, s[68:69]
	global_load_dwordx4 v[104:107], v1, s[66:67]
	global_load_dwordx4 v[108:111], v1, s[66:67] offset:1024
	v_pk_fma_f32 v[136:137], v[8:9], v[168:169], v[136:137]
	v_pk_fma_f32 v[138:139], v[10:11], v[170:171], v[138:139]
	v_pk_fma_f32 v[140:141], v[12:13], v[172:173], v[140:141]
	v_pk_fma_f32 v[142:143], v[14:15], v[174:175], v[142:143]
	v_pk_fma_f32 v[144:145], v[16:17], v[176:177], v[144:145]
	v_pk_fma_f32 v[146:147], v[18:19], v[178:179], v[146:147]
	v_pk_fma_f32 v[148:149], v[20:21], v[180:181], v[148:149]
	v_pk_fma_f32 v[150:151], v[22:23], v[182:183], v[150:151]
	v_pk_mul_f32 v[154:155], v[136:137], v[136:137]
	v_pk_add_f32 v[152:153], v[136:137], v[138:139]
	v_pk_fma_f32 v[154:155], v[138:139], v[138:139], v[154:155]
	v_pk_add_f32 v[152:153], v[152:153], v[140:141]
	v_pk_fma_f32 v[154:155], v[140:141], v[140:141], v[154:155]
	v_pk_add_f32 v[152:153], v[152:153], v[142:143]
	v_pk_fma_f32 v[154:155], v[142:143], v[142:143], v[154:155]
	v_pk_add_f32 v[152:153], v[152:153], v[144:145]
; __device__ __forceinline__ float wave_sum_dpp(float v) {
;     v += __builtin_bit_cast(float, __builtin_amdgcn_update_dpp(0, __builtin_bit_cast(int, v), 0x111, 0xf, 0xf, true));
;     v += __builtin_bit_cast(float, __builtin_amdgcn_update_dpp(0, __builtin_bit_cast(int, v), 0x112, 0xf, 0xf, true));
;     v += __builtin_bit_cast(float, __builtin_amdgcn_update_dpp(0, __builtin_bit_cast(int, v), 0x114, 0xf, 0xf, true));
;     v += __builtin_bit_cast(float, __builtin_amdgcn_update_dpp(0, __builtin_bit_cast(int, v), 0x118, 0xf, 0xf, true));
;     v += __builtin_bit_cast(float, __builtin_amdgcn_update_dpp(0, __builtin_bit_cast(int, v), 0x142, 0xa, 0xf, false));
;     v += __builtin_bit_cast(float, __builtin_amdgcn_update_dpp(0, __builtin_bit_cast(int, v), 0x143, 0xc, 0xf, false));
;     return __builtin_bit_cast(float, __builtin_amdgcn_readlane(__builtin_bit_cast(int, v), 63));
; __device__ void phase_resid_ln(PP P, int wid, int layer, int sub, const bf16_t* usrc, const bf16_t* msrc, bf16_t* Adst) {
;     ...
; #pragma unroll
;         for (int rr = 0; rr < 2; ++rr) {
;             if (rr < nr) {
;                 const int r = row + rr * 8;
;                 const float ts = wave_sum_dpp(sum[rr]), tq = wave_sum_dpp(sq[rr]);
;                 const float mu = ts * (1.f / D), var = fmaxf(tq * (1.f / D) - mu * mu, 0.f), rstd = rsqrtf(var + LN_EPS);
; #pragma unroll
;                 for (int h = 0; h < 2; ++h) {
;                     const int c8 = h * 512 + lane * 8; float xn[8];
; #pragma unroll
;                     for (int e = 0; e < 8; ++e) xn[e] = (y[rr][h * 8 + e] - mu) * rstd * gm[h * 8 + e] + bt[h * 8 + e];
;                     if (has_next) { float u[8];
; #pragma unroll
;                         for (int e = 0; e < 8; ++e) u[e] = xn[e] * nsc[h * 8 + e] + nsh[h * 8 + e];
;                         store_A(Adst, xlayout, r, c8, u); }
;                     else store8f(P->out + (size_t)r * D + c8, xn);
;                 }
;             }
;         }
;         if (nr == 1 && row2 < rend) row -= 8;
	v_pk_fma_f32 v[154:155], v[144:145], v[144:145], v[154:155]
	v_pk_add_f32 v[152:153], v[152:153], v[146:147]
	v_pk_fma_f32 v[154:155], v[146:147], v[146:147], v[154:155]
	v_pk_add_f32 v[152:153], v[152:153], v[148:149]
	v_pk_fma_f32 v[154:155], v[148:149], v[148:149], v[154:155]
	v_pk_add_f32 v[152:153], v[152:153], v[150:151]
	v_pk_fma_f32 v[154:155], v[150:151], v[150:151], v[154:155]
	s_nop 0
	v_add_f32_e32 v156, v152, v153
	v_add_f32_e32 v157, v154, v155
	v_mov_b32_e32 v192, 0
	v_mov_b32_e32 v193, 0
	v_add_f32_dpp v156, v156, v156 row_shr:1 row_mask:0xf bank_mask:0xf bound_ctrl:1
	v_add_f32_dpp v157, v157, v157 row_shr:1 row_mask:0xf bank_mask:0xf bound_ctrl:1
	s_nop 1
	v_add_f32_dpp v156, v156, v156 row_shr:2 row_mask:0xf bank_mask:0xf bound_ctrl:1
	v_add_f32_dpp v157, v157, v157 row_shr:2 row_mask:0xf bank_mask:0xf bound_ctrl:1
	s_nop 1
	v_add_f32_dpp v156, v156, v156 row_shr:4 row_mask:0xf bank_mask:0xf bound_ctrl:1
	v_add_f32_dpp v157, v157, v157 row_shr:4 row_mask:0xf bank_mask:0xf bound_ctrl:1
	s_nop 1
	v_add_f32_dpp v156, v156, v156 row_shr:8 row_mask:0xf bank_mask:0xf bound_ctrl:1
	v_add_f32_dpp v157, v157, v157 row_shr:8 row_mask:0xf bank_mask:0xf bound_ctrl:1
	s_nop 1
	v_mov_b32_dpp v192, v156 row_bcast:15 row_mask:0xa bank_mask:0xf
	v_mov_b32_dpp v193, v157 row_bcast:15 row_mask:0xa bank_mask:0xf
	s_nop 0
	v_add_f32_e32 v156, v156, v192
	v_add_f32_e32 v157, v157, v193
	v_mov_b32_e32 v192, 0
	v_mov_b32_e32 v193, 0
	s_nop 1
	v_mov_b32_dpp v192, v156 row_bcast:31 row_mask:0xc bank_mask:0xf
	v_mov_b32_dpp v193, v157 row_bcast:31 row_mask:0xc bank_mask:0xf
	s_nop 0
	v_add_f32_e32 v156, v156, v192
	v_add_f32_e32 v157, v157, v193
	s_nop 1
	v_readlane_b32 s8, v156, 63
	v_readlane_b32 s9, v157, 63
	s_nop 3
	v_mul_f32_e32 v162, s8, v166
	v_mul_f32_e32 v160, s9, v166
	v_fma_f32 v160, -v162, v162, v160
	v_max_f32_e32 v160, 0, v160
	v_add_f32_e32 v160, 0x3727c5ac, v160
	v_rsq_f32_e32 v158, v160
	s_nop 1
	v_mul_f32_e64 v160, -v162, v158
	s_nop 0
	v_pk_fma_f32 v[136:137], v[136:137], v[158:159], v[160:161] op_sel_hi:[1,0,0]
	v_pk_fma_f32 v[138:139], v[138:139], v[158:159], v[160:161] op_sel_hi:[1,0,0]
	v_pk_fma_f32 v[140:141], v[140:141], v[158:159], v[160:161] op_sel_hi:[1,0,0]
	v_pk_fma_f32 v[142:143], v[142:143], v[158:159], v[160:161] op_sel_hi:[1,0,0]
	v_pk_fma_f32 v[144:145], v[144:145], v[158:159], v[160:161] op_sel_hi:[1,0,0]
	v_pk_fma_f32 v[146:147], v[146:147], v[158:159], v[160:161] op_sel_hi:[1,0,0]
	v_pk_fma_f32 v[148:149], v[148:149], v[158:159], v[160:161] op_sel_hi:[1,0,0]
	v_pk_fma_f32 v[150:151], v[150:151], v[158:159], v[160:161] op_sel_hi:[1,0,0]
	v_pk_fma_f32 v[136:137], v[136:137], v[56:57], v[72:73]
	v_pk_fma_f32 v[138:139], v[138:139], v[58:59], v[74:75]
	v_pk_fma_f32 v[140:141], v[140:141], v[60:61], v[76:77]
	v_pk_fma_f32 v[142:143], v[142:143], v[62:63], v[78:79]
	v_pk_fma_f32 v[144:145], v[144:145], v[64:65], v[80:81]
	v_pk_fma_f32 v[146:147], v[146:147], v[66:67], v[82:83]
	v_pk_fma_f32 v[148:149], v[148:149], v[68:69], v[84:85]
	v_pk_fma_f32 v[150:151], v[150:151], v[70:71], v[86:87]
	s_nop 0
	v_cvt_pk_bf16_f32 v184, v136, v137
	v_cvt_pk_bf16_f32 v185, v138, v139
	v_cvt_pk_bf16_f32 v186, v140, v141
	v_cvt_pk_bf16_f32 v187, v142, v143
	v_cvt_pk_bf16_f32 v188, v144, v145
	v_cvt_pk_bf16_f32 v189, v146, v147
	v_cvt_pk_bf16_f32 v190, v148, v149
	v_cvt_pk_bf16_f32 v191, v150, v151
	s_lshl_b32 s4, s64, 11
	s_lshr_b32 s5, s64, 5
	s_mul_i32 s5, s5, 0x600
	s_and_b32 s6, s64, 31
	s_lshl_b32 s6, s6, 5
	s_add_i32 s5, s5, s6
	s_cmp_lg_u32 s74, 0
	s_cselect_b32 s4, s5, s4
	s_add_u32 s68, s62, s4
	s_addc_u32 s69, s63, 0
	global_store_dwordx4 v4, v[184:187], s[68:69]
	global_store_dwordx4 v5, v[188:191], s[68:69]
	s_add_i32 s88, s64, 8
	s_cmp_lt_u32 s88, s46
	s_cbranch_scc0 .Lrl_done
	s_lshr_b32 s4, s88, 11
	s_cmp_eq_u32 s4, s65
	s_cbranch_scc1 .Lrl_N_okB
	s_mov_b32 s91, 1
	s_branch .Lrl_par_N
.Lrl_N_okB:
	s_waitcnt vmcnt(8)
	v_lshlrev_b32_e32 v168, 16, v112
	v_and_b32_e32 v169, s75, v112
	v_lshlrev_b32_e32 v170, 16, v113
	v_and_b32_e32 v171, s75, v113
	v_lshlrev_b32_e32 v172, 16, v114
	v_and_b32_e32 v173, s75, v114
	v_lshlrev_b32_e32 v174, 16, v115
	v_and_b32_e32 v175, s75, v115
	v_lshlrev_b32_e32 v176, 16, v116
	v_and_b32_e32 v177, s75, v116
	v_lshlrev_b32_e32 v178, 16, v117
	v_and_b32_e32 v179, s75, v117
	v_lshlrev_b32_e32 v180, 16, v118
	v_and_b32_e32 v181, s75, v118
	v_lshlrev_b32_e32 v182, 16, v119
	v_and_b32_e32 v183, s75, v119
	v_pk_fma_f32 v[136:137], v[168:169], v[24:25], v[40:41]
	v_pk_fma_f32 v[138:139], v[170:171], v[26:27], v[42:43]
	v_pk_fma_f32 v[140:141], v[172:173], v[28:29], v[44:45]
	v_pk_fma_f32 v[142:143], v[174:175], v[30:31], v[46:47]
	v_pk_fma_f32 v[144:145], v[176:177], v[32:33], v[48:49]
	v_pk_fma_f32 v[146:147], v[178:179], v[34:35], v[50:51]
	v_pk_fma_f32 v[148:149], v[180:181], v[36:37], v[52:53]
	v_pk_fma_f32 v[150:151], v[182:183], v[38:39], v[54:55]
	v_lshlrev_b32_e32 v168, 16, v128
	v_and_b32_e32 v169, s75, v128
	v_lshlrev_b32_e32 v170, 16, v129
	v_and_b32_e32 v171, s75, v129
	v_lshlrev_b32_e32 v172, 16, v130
	v_and_b32_e32 v173, s75, v130
	v_lshlrev_b32_e32 v174, 16, v131
	v_and_b32_e32 v175, s75, v131
	v_lshlrev_b32_e32 v176, 16, v132
	v_and_b32_e32 v177, s75, v132
	v_lshlrev_b32_e32 v178, 16, v133
	v_and_b32_e32 v179, s75, v133
	v_lshlrev_b32_e32 v180, 16, v134
	v_and_b32_e32 v181, s75, v134
	v_lshlrev_b32_e32 v182, 16, v135
	v_and_b32_e32 v183, s75, v135
	s_add_i32 s89, s88, 16
	s_cmp_lt_u32 s89, s46
	s_cselect_b32 s89, s89, s88
	s_lshl_b32 s4, s89, 11
	s_lshr_b32 s5, s89, 5
	s_mul_i32 s5, s5, 0x600
	s_and_b32 s6, s89, 31
	s_lshl_b32 s6, s6, 5
	s_add_i32 s5, s5, s6
	s_cmp_lg_u32 s73, 0
; __device__ void phase_resid_ln(PP P, int wid, int layer, int sub, const bf16_t* usrc, const bf16_t* msrc, bf16_t* Adst) {
;     ...
;         const int row2 = row + 8;
;         const int nr = (row2 < rend && (row2 >> 11) == seq) ? 2 : 1;
;         float y[2][16], sum[2] = {0.f, 0.f}, sq[2] = {0.f, 0.f};
; #pragma unroll
;         for (int rr = 0; rr < 2; ++rr) {
;             if (rr < nr) {
;                 const int r = row + rr * 8;
; #pragma unroll
;                 for (int h = 0; h < 2; ++h) {
;                     const int c8 = h * 512 + lane * 8; float x[8], m[8];
;                     if (x_from_input) load8f(xin_row(P, r) + c8, x);
;                     else { float u[8]; load_A(usrc, src_xlayout, r, c8, u);
; #pragma unroll
;                         for (int e = 0; e < 8; ++e) x[e] = (u[e] - sh[h * 8 + e]) * sc[h * 8 + e]; }
;                     unpack8(*(const u32x4*)(msrc + (size_t)r * D + c8), m);
; #pragma unroll
;                     for (int e = 0; e < 8; ++e) { const float v = ALPHA * x[e] + gt[h * 8 + e] * m[e]; y[rr][h * 8 + e] = v; sum[rr] += v; sq[rr] += v * v; }
;                 }
;             }
;         }
; #pragma unroll
;         for (int rr = 0; rr < 2; ++rr) {
;             if (rr < nr) {
;                 const int r = row + rr * 8;
;                 const float ts = wave_sum_dpp(sum[rr]), tq = wave_sum_dpp(sq[rr]);
;                 const float mu = ts * (1.f / D), var = fmaxf(tq * (1.f / D) - mu * mu, 0.f), rstd = rsqrtf(var + LN_EPS);
; #pragma unroll
;                 for (int h = 0; h < 2; ++h) {
;                     const int c8 = h * 512 + lane * 8; float xn[8];
; #pragma unroll
;                     for (int e = 0; e < 8; ++e) xn[e] = (y[rr][h * 8 + e] - mu) * rstd * gm[h * 8 + e] + bt[h * 8 + e];
;                     if (has_next) { float u[8];
; #pragma unroll
;                         for (int e = 0; e < 8; ++e) u[e] = xn[e] * nsc[h * 8 + e] + nsh[h * 8 + e];
;                         store_A(Adst, xlayout, r, c8, u); }
;                     else store8f(P->out + (size_t)r * D + c8, xn);
;                 }
;             }
;         }
;         if (nr == 1 && row2 < rend) row -= 8;
	s_cselect_b32 s5, s5, s4
	s_add_u32 s68, s60, s5
	s_addc_u32 s69, s61, 0
	s_add_u32 s66, s76, s4
	s_addc_u32 s67, s77, 0
	global_load_dwordx4 v[112:115], v2, s[68:69]
	global_load_dwordx4 v[116:119], v3, s[68:69]
	global_load_dwordx4 v[128:131], v1, s[66:67]
	global_load_dwordx4 v[132:135], v1, s[66:67] offset:1024
	v_pk_fma_f32 v[136:137], v[8:9], v[168:169], v[136:137]
	v_pk_fma_f32 v[138:139], v[10:11], v[170:171], v[138:139]
	v_pk_fma_f32 v[140:141], v[12:13], v[172:173], v[140:141]
	v_pk_fma_f32 v[142:143], v[14:15], v[174:175], v[142:143]
	v_pk_fma_f32 v[144:145], v[16:17], v[176:177], v[144:145]
	v_pk_fma_f32 v[146:147], v[18:19], v[178:179], v[146:147]
	v_pk_fma_f32 v[148:149], v[20:21], v[180:181], v[148:149]
	v_pk_fma_f32 v[150:151], v[22:23], v[182:183], v[150:151]
	v_pk_mul_f32 v[154:155], v[136:137], v[136:137]
	v_pk_add_f32 v[152:153], v[136:137], v[138:139]
	v_pk_fma_f32 v[154:155], v[138:139], v[138:139], v[154:155]
	v_pk_add_f32 v[152:153], v[152:153], v[140:141]
	v_pk_fma_f32 v[154:155], v[140:141], v[140:141], v[154:155]
	v_pk_add_f32 v[152:153], v[152:153], v[142:143]
	v_pk_fma_f32 v[154:155], v[142:143], v[142:143], v[154:155]
	v_pk_add_f32 v[152:153], v[152:153], v[144:145]
	v_pk_fma_f32 v[154:155], v[144:145], v[144:145], v[154:155]
	v_pk_add_f32 v[152:153], v[152:153], v[146:147]
	v_pk_fma_f32 v[154:155], v[146:147], v[146:147], v[154:155]
	v_pk_add_f32 v[152:153], v[152:153], v[148:149]
	v_pk_fma_f32 v[154:155], v[148:149], v[148:149], v[154:155]
	v_pk_add_f32 v[152:153], v[152:153], v[150:151]
	v_pk_fma_f32 v[154:155], v[150:151], v[150:151], v[154:155]
	s_nop 0
	v_add_f32_e32 v156, v152, v153
	v_add_f32_e32 v157, v154, v155
	v_mov_b32_e32 v192, 0
	v_mov_b32_e32 v193, 0
	v_add_f32_dpp v156, v156, v156 row_shr:1 row_mask:0xf bank_mask:0xf bound_ctrl:1
	v_add_f32_dpp v157, v157, v157 row_shr:1 row_mask:0xf bank_mask:0xf bound_ctrl:1
	s_nop 1
	v_add_f32_dpp v156, v156, v156 row_shr:2 row_mask:0xf bank_mask:0xf bound_ctrl:1
	v_add_f32_dpp v157, v157, v157 row_shr:2 row_mask:0xf bank_mask:0xf bound_ctrl:1
	s_nop 1
	v_add_f32_dpp v156, v156, v156 row_shr:4 row_mask:0xf bank_mask:0xf bound_ctrl:1
	v_add_f32_dpp v157, v157, v157 row_shr:4 row_mask:0xf bank_mask:0xf bound_ctrl:1
	s_nop 1
	v_add_f32_dpp v156, v156, v156 row_shr:8 row_mask:0xf bank_mask:0xf bound_ctrl:1
	v_add_f32_dpp v157, v157, v157 row_shr:8 row_mask:0xf bank_mask:0xf bound_ctrl:1
	s_nop 1
	v_mov_b32_dpp v192, v156 row_bcast:15 row_mask:0xa bank_mask:0xf
	v_mov_b32_dpp v193, v157 row_bcast:15 row_mask:0xa bank_mask:0xf
	s_nop 0
	v_add_f32_e32 v156, v156, v192
	v_add_f32_e32 v157, v157, v193
	v_mov_b32_e32 v192, 0
	v_mov_b32_e32 v193, 0
	s_nop 1
	v_mov_b32_dpp v192, v156 row_bcast:31 row_mask:0xc bank_mask:0xf
	v_mov_b32_dpp v193, v157 row_bcast:31 row_mask:0xc bank_mask:0xf
	s_nop 0
	v_add_f32_e32 v156, v156, v192
	v_add_f32_e32 v157, v157, v193
	s_nop 1
	v_readlane_b32 s8, v156, 63
	v_readlane_b32 s9, v157, 63
	s_nop 3
	v_mul_f32_e32 v162, s8, v166
	v_mul_f32_e32 v160, s9, v166
	v_fma_f32 v160, -v162, v162, v160
	v_max_f32_e32 v160, 0, v160
	v_add_f32_e32 v160, 0x3727c5ac, v160
	v_rsq_f32_e32 v158, v160
	s_nop 1
	v_mul_f32_e64 v160, -v162, v158
	s_nop 0
	v_pk_fma_f32 v[136:137], v[136:137], v[158:159], v[160:161] op_sel_hi:[1,0,0]
	v_pk_fma_f32 v[138:139], v[138:139], v[158:159], v[160:161] op_sel_hi:[1,0,0]
	v_pk_fma_f32 v[140:141], v[140:141], v[158:159], v[160:161] op_sel_hi:[1,0,0]
	v_pk_fma_f32 v[142:143], v[142:143], v[158:159], v[160:161] op_sel_hi:[1,0,0]
	v_pk_fma_f32 v[144:145], v[144:145], v[158:159], v[160:161] op_sel_hi:[1,0,0]
	v_pk_fma_f32 v[146:147], v[146:147], v[158:159], v[160:161] op_sel_hi:[1,0,0]
	v_pk_fma_f32 v[148:149], v[148:149], v[158:159], v[160:161] op_sel_hi:[1,0,0]
	v_pk_fma_f32 v[150:151], v[150:151], v[158:159], v[160:161] op_sel_hi:[1,0,0]
	v_pk_fma_f32 v[136:137], v[136:137], v[56:57], v[72:73]
	v_pk_fma_f32 v[138:139], v[138:139], v[58:59], v[74:75]
	v_pk_fma_f32 v[140:141], v[140:141], v[60:61], v[76:77]
	v_pk_fma_f32 v[142:143], v[142:143], v[62:63], v[78:79]
	v_pk_fma_f32 v[144:145], v[144:145], v[64:65], v[80:81]
	v_pk_fma_f32 v[146:147], v[146:147], v[66:67], v[82:83]
	v_pk_fma_f32 v[148:149], v[148:149], v[68:69], v[84:85]
	v_pk_fma_f32 v[150:151], v[150:151], v[70:71], v[86:87]
	s_nop 0
	v_cvt_pk_bf16_f32 v184, v136, v137
	v_cvt_pk_bf16_f32 v185, v138, v139
	v_cvt_pk_bf16_f32 v186, v140, v141
	v_cvt_pk_bf16_f32 v187, v142, v143
	v_cvt_pk_bf16_f32 v188, v144, v145
	v_cvt_pk_bf16_f32 v189, v146, v147
	v_cvt_pk_bf16_f32 v190, v148, v149
	v_cvt_pk_bf16_f32 v191, v150, v151
	s_lshl_b32 s4, s88, 11
	s_lshr_b32 s5, s88, 5
	s_mul_i32 s5, s5, 0x600
	s_and_b32 s6, s88, 31
	s_lshl_b32 s6, s6, 5
	s_add_i32 s5, s5, s6
	s_cmp_lg_u32 s74, 0
	s_cselect_b32 s4, s5, s4
	s_add_u32 s68, s62, s4
	s_addc_u32 s69, s63, 0
	global_store_dwordx4 v4, v[184:187], s[68:69]
	global_store_dwordx4 v5, v[188:191], s[68:69]
	s_add_i32 s64, s64, 16
	s_cmp_lt_u32 s64, s46
	s_cbranch_scc1 .Lrl_N_loop
	s_branch .Lrl_done
; __device__ void phase_resid_ln(PP P, int wid, int layer, int sub, const bf16_t* usrc, const bf16_t* msrc, bf16_t* Adst) {
;     ...
;         if (seq != cur_seq) {
;             cur_seq = seq;
;             const float* mrow = mod + (size_t)(layer * NSEQ + seq) * 6 * D;
;             const float* nmrow = mod + (size_t)((has_next ? nl : 0) * NSEQ + seq) * 6 * D;
; #pragma unroll
;             for (int h = 0; h < 2; ++h) { const int c8 = h * 512 + lane * 8; float t[8];
;                 load8f(mrow + (sub == 0 ? 2 : 5) * D + c8, t);
; #pragma unroll
;                 for (int e = 0; e < 8; ++e) gt[h * 8 + e] = 1.f + t[e];
;                 load8f(mrow + (sub == 0 ? 0 : 3) * D + c8, t);
; #pragma unroll
;                 for (int e = 0; e < 8; ++e) sh[h * 8 + e] = t[e];
;                 load8f(mrow + (sub == 0 ? 1 : 4) * D + c8, t);
; #pragma unroll
;                 for (int e = 0; e < 8; ++e) sc[h * 8 + e] = __builtin_amdgcn_rcpf(1.f + t[e]);
;                 load8f(nmrow + (nsub == 0 ? 0 : 3) * D + c8, t);
; #pragma unroll
;                 for (int e = 0; e < 8; ++e) nsh[h * 8 + e] = t[e];
;                 load8f(nmrow + (nsub == 0 ? 1 : 4) * D + c8, t);
; #pragma unroll
;                 for (int e = 0; e < 8; ++e) nsc[h * 8 + e] = 1.f + t[e]; }
;         }
.Lrl_par_N:
	s_mov_b32 s65, s4
	s_mul_i32 s5, s25, 40
	s_add_i32 s5, s5, s4
	s_mul_i32 s5, s5, 0x6000
	s_mul_i32 s6, s72, 0x3000
	s_add_i32 s5, s5, s6
	s_add_u32 s6, s70, s5
	s_addc_u32 s7, s71, 0
	s_add_u32 s8, s6, 0x1000
	s_addc_u32 s9, s7, 0
	s_add_u32 s10, s6, 0x2000
	s_addc_u32 s11, s7, 0
	global_load_dwordx4 v[40:43], v6, s[6:7]
	global_load_dwordx4 v[44:47], v6, s[6:7] offset:16
	global_load_dwordx4 v[48:51], v6, s[6:7] offset:2048
	global_load_dwordx4 v[52:55], v6, s[6:7] offset:2064
	global_load_dwordx4 v[24:27], v6, s[8:9]
	global_load_dwordx4 v[28:31], v6, s[8:9] offset:16
	global_load_dwordx4 v[32:35], v6, s[8:9] offset:2048
	global_load_dwordx4 v[36:39], v6, s[8:9] offset:2064
	global_load_dwordx4 v[8:11], v6, s[10:11]
	global_load_dwordx4 v[12:15], v6, s[10:11] offset:16
	global_load_dwordx4 v[16:19], v6, s[10:11] offset:2048
	global_load_dwordx4 v[20:23], v6, s[10:11] offset:2064
	s_add_i32 s5, s25, s72
	s_mul_i32 s5, s5, 40
	s_add_i32 s5, s5, s4
	s_mul_i32 s5, s5, 0x6000
	s_xor_b32 s6, s72, 1
	s_mul_i32 s6, s6, 0x3000
	s_add_i32 s5, s5, s6
	s_add_u32 s6, s70, s5
	s_addc_u32 s7, s71, 0
	s_add_u32 s8, s6, 0x1000
	s_addc_u32 s9, s7, 0
	global_load_dwordx4 v[72:75], v6, s[6:7]
	global_load_dwordx4 v[76:79], v6, s[6:7] offset:16
	global_load_dwordx4 v[80:83], v6, s[6:7] offset:2048
	global_load_dwordx4 v[84:87], v6, s[6:7] offset:2064
	global_load_dwordx4 v[56:59], v6, s[8:9]
	global_load_dwordx4 v[60:63], v6, s[8:9] offset:16
	global_load_dwordx4 v[64:67], v6, s[8:9] offset:2048
	global_load_dwordx4 v[68:71], v6, s[8:9] offset:2064
	global_load_dwordx4 v[168:171], v6, s[80:81]
	global_load_dwordx4 v[172:175], v6, s[80:81] offset:16
	global_load_dwordx4 v[176:179], v6, s[80:81] offset:2048
	global_load_dwordx4 v[180:183], v6, s[80:81] offset:2064
	global_load_dwordx4 v[136:139], v6, s[82:83]
	global_load_dwordx4 v[140:143], v6, s[82:83] offset:16
	global_load_dwordx4 v[144:147], v6, s[82:83] offset:2048
	global_load_dwordx4 v[148:151], v6, s[82:83] offset:2064
	s_waitcnt vmcnt(0)
	v_pk_add_f32 v[8:9], v[8:9], 1.0 op_sel_hi:[1,0]
	v_pk_add_f32 v[10:11], v[10:11], 1.0 op_sel_hi:[1,0]
	v_pk_add_f32 v[12:13], v[12:13], 1.0 op_sel_hi:[1,0]
	v_pk_add_f32 v[14:15], v[14:15], 1.0 op_sel_hi:[1,0]
	v_pk_add_f32 v[16:17], v[16:17], 1.0 op_sel_hi:[1,0]
	v_pk_add_f32 v[18:19], v[18:19], 1.0 op_sel_hi:[1,0]
	v_pk_add_f32 v[20:21], v[20:21], 1.0 op_sel_hi:[1,0]
	v_pk_add_f32 v[22:23], v[22:23], 1.0 op_sel_hi:[1,0]
	v_pk_add_f32 v[24:25], v[24:25], 1.0 op_sel_hi:[1,0]
	v_pk_add_f32 v[26:27], v[26:27], 1.0 op_sel_hi:[1,0]
	v_pk_add_f32 v[28:29], v[28:29], 1.0 op_sel_hi:[1,0]
	v_pk_add_f32 v[30:31], v[30:31], 1.0 op_sel_hi:[1,0]
	v_pk_add_f32 v[32:33], v[32:33], 1.0 op_sel_hi:[1,0]
	v_pk_add_f32 v[34:35], v[34:35], 1.0 op_sel_hi:[1,0]
	v_pk_add_f32 v[36:37], v[36:37], 1.0 op_sel_hi:[1,0]
	v_pk_add_f32 v[38:39], v[38:39], 1.0 op_sel_hi:[1,0]
	v_rcp_f32_e32 v24, v24
	v_rcp_f32_e32 v25, v25
	v_rcp_f32_e32 v26, v26
	v_rcp_f32_e32 v27, v27
	v_rcp_f32_e32 v28, v28
	v_rcp_f32_e32 v29, v29
	v_rcp_f32_e32 v30, v30
	v_rcp_f32_e32 v31, v31
	v_rcp_f32_e32 v32, v32
	v_rcp_f32_e32 v33, v33
	v_rcp_f32_e32 v34, v34
	v_rcp_f32_e32 v35, v35
	v_rcp_f32_e32 v36, v36
	v_rcp_f32_e32 v37, v37
	v_rcp_f32_e32 v38, v38
	v_rcp_f32_e32 v39, v39
	v_pk_mul_f32 v[24:25], v[24:25], s[36:37] op_sel_hi:[1,0]
	v_pk_mul_f32 v[26:27], v[26:27], s[36:37] op_sel_hi:[1,0]
	v_pk_mul_f32 v[28:29], v[28:29], s[36:37] op_sel_hi:[1,0]
	v_pk_mul_f32 v[30:31], v[30:31], s[36:37] op_sel_hi:[1,0]
	v_pk_mul_f32 v[32:33], v[32:33], s[36:37] op_sel_hi:[1,0]
	v_pk_mul_f32 v[34:35], v[34:35], s[36:37] op_sel_hi:[1,0]
	v_pk_mul_f32 v[36:37], v[36:37], s[36:37] op_sel_hi:[1,0]
	v_pk_mul_f32 v[38:39], v[38:39], s[36:37] op_sel_hi:[1,0]
	v_pk_mul_f32 v[40:41], v[40:41], v[24:25] neg_lo:[1,0] neg_hi:[1,0]
	v_pk_mul_f32 v[42:43], v[42:43], v[26:27] neg_lo:[1,0] neg_hi:[1,0]
	v_pk_mul_f32 v[44:45], v[44:45], v[28:29] neg_lo:[1,0] neg_hi:[1,0]
	v_pk_mul_f32 v[46:47], v[46:47], v[30:31] neg_lo:[1,0] neg_hi:[1,0]
	v_pk_mul_f32 v[48:49], v[48:49], v[32:33] neg_lo:[1,0] neg_hi:[1,0]
	v_pk_mul_f32 v[50:51], v[50:51], v[34:35] neg_lo:[1,0] neg_hi:[1,0]
	v_pk_mul_f32 v[52:53], v[52:53], v[36:37] neg_lo:[1,0] neg_hi:[1,0]
	v_pk_mul_f32 v[54:55], v[54:55], v[38:39] neg_lo:[1,0] neg_hi:[1,0]
	v_pk_add_f32 v[56:57], v[56:57], 1.0 op_sel_hi:[1,0]
	v_pk_add_f32 v[58:59], v[58:59], 1.0 op_sel_hi:[1,0]
	v_pk_add_f32 v[60:61], v[60:61], 1.0 op_sel_hi:[1,0]
	v_pk_add_f32 v[62:63], v[62:63], 1.0 op_sel_hi:[1,0]
	v_pk_add_f32 v[64:65], v[64:65], 1.0 op_sel_hi:[1,0]
	v_pk_add_f32 v[66:67], v[66:67], 1.0 op_sel_hi:[1,0]
	v_pk_add_f32 v[68:69], v[68:69], 1.0 op_sel_hi:[1,0]
	v_pk_add_f32 v[70:71], v[70:71], 1.0 op_sel_hi:[1,0]
	v_pk_fma_f32 v[72:73], v[136:137], v[56:57], v[72:73]
	v_pk_fma_f32 v[74:75], v[138:139], v[58:59], v[74:75]
	v_pk_fma_f32 v[76:77], v[140:141], v[60:61], v[76:77]
	v_pk_fma_f32 v[78:79], v[142:143], v[62:63], v[78:79]
	v_pk_fma_f32 v[80:81], v[144:145], v[64:65], v[80:81]
	v_pk_fma_f32 v[82:83], v[146:147], v[66:67], v[82:83]
	v_pk_fma_f32 v[84:85], v[148:149], v[68:69], v[84:85]
	v_pk_fma_f32 v[86:87], v[150:151], v[70:71], v[86:87]
	v_pk_mul_f32 v[56:57], v[56:57], v[168:169]
	v_pk_mul_f32 v[58:59], v[58:59], v[170:171]
	v_pk_mul_f32 v[60:61], v[60:61], v[172:173]
	v_pk_mul_f32 v[62:63], v[62:63], v[174:175]
	v_pk_mul_f32 v[64:65], v[64:65], v[176:177]
	v_pk_mul_f32 v[66:67], v[66:67], v[178:179]
	v_pk_mul_f32 v[68:69], v[68:69], v[180:181]
	v_pk_mul_f32 v[70:71], v[70:71], v[182:183]
	s_nop 1
	s_cmp_eq_u32 s91, 0
	s_cbranch_scc1 .Lrl_N_okA
	s_branch .Lrl_N_okB
.Lrl_X_start:
	s_lshl_b32 s4, s64, 11
	s_lshl_b32 s5, s64, 12
	s_sub_u32 s6, s5, 0x10000000
	s_cmp_lt_u32 s64, 0x10000
	s_cselect_b32 s5, s5, s6
	s_cselect_b32 s6, s84, s86
	s_cselect_b32 s7, s85, s87
	s_add_u32 s68, s6, s5
	s_addc_u32 s69, s7, 0
	s_add_u32 s66, s76, s4
	s_addc_u32 s67, s77, 0
	global_load_dwordx4 v[88:91], v6, s[68:69]
	global_load_dwordx4 v[92:95], v6, s[68:69] offset:16
	global_load_dwordx4 v[96:99], v6, s[68:69] offset:2048
	global_load_dwordx4 v[100:103], v6, s[68:69] offset:2064
	global_load_dwordx4 v[104:107], v1, s[66:67]
	global_load_dwordx4 v[108:111], v1, s[66:67] offset:1024
	s_add_i32 s88, s64, 8
	s_cmp_lt_u32 s88, s46
	s_cselect_b32 s89, s88, s64
	s_lshl_b32 s4, s89, 11
	s_lshl_b32 s5, s89, 12
	s_sub_u32 s6, s5, 0x10000000
	s_cmp_lt_u32 s89, 0x10000
	s_cselect_b32 s5, s5, s6
	s_cselect_b32 s6, s84, s86
	s_cselect_b32 s7, s85, s87
	s_add_u32 s68, s6, s5
	s_addc_u32 s69, s7, 0
	s_add_u32 s66, s76, s4
	s_addc_u32 s67, s77, 0
	global_load_dwordx4 v[112:115], v6, s[68:69]
	global_load_dwordx4 v[116:119], v6, s[68:69] offset:16
	global_load_dwordx4 v[120:123], v6, s[68:69] offset:2048
	global_load_dwordx4 v[124:127], v6, s[68:69] offset:2064
	global_load_dwordx4 v[128:131], v1, s[66:67]
	global_load_dwordx4 v[132:135], v1, s[66:67] offset:1024

; __device__ void phase_resid_ln(PP P, int wid, int layer, int sub, const bf16_t* usrc, const bf16_t* msrc, bf16_t* Adst) {
;     ...
;         const int row2 = row + 8;
;         const int nr = (row2 < rend && (row2 >> 11) == seq) ? 2 : 1;
;         float y[2][16], sum[2] = {0.f, 0.f}, sq[2] = {0.f, 0.f};
; #pragma unroll
;         for (int rr = 0; rr < 2; ++rr) {
;             if (rr < nr) {
;                 const int r = row + rr * 8;
; #pragma unroll
;                 for (int h = 0; h < 2; ++h) {
;                     const int c8 = h * 512 + lane * 8; float x[8], m[8];
;                     if (x_from_input) load8f(xin_row(P, r) + c8, x);
;                     else { float u[8]; load_A(usrc, src_xlayout, r, c8, u);
; #pragma unroll
;                         for (int e = 0; e < 8; ++e) x[e] = (u[e] - sh[h * 8 + e]) * sc[h * 8 + e]; }
;                     unpack8(*(const u32x4*)(msrc + (size_t)r * D + c8), m);
; #pragma unroll
;                     for (int e = 0; e < 8; ++e) { const float v = ALPHA * x[e] + gt[h * 8 + e] * m[e]; y[rr][h * 8 + e] = v; sum[rr] += v; sq[rr] += v * v; }
;                 }
;             }
;         }
; #pragma unroll
;         for (int rr = 0; rr < 2; ++rr) {
;             if (rr < nr) {
;                 const int r = row + rr * 8;
;                 const float ts = wave_sum_dpp(sum[rr]), tq = wave_sum_dpp(sq[rr]);
;                 const float mu = ts * (1.f / D), var = fmaxf(tq * (1.f / D) - mu * mu, 0.f), rstd = rsqrtf(var + LN_EPS);
; #pragma unroll
;                 for (int h = 0; h < 2; ++h) {
;                     const int c8 = h * 512 + lane * 8; float xn[8];
; #pragma unroll
;                     for (int e = 0; e < 8; ++e) xn[e] = (y[rr][h * 8 + e] - mu) * rstd * gm[h * 8 + e] + bt[h * 8 + e];
;                     if (has_next) { float u[8];
; #pragma unroll
;                         for (int e = 0; e < 8; ++e) u[e] = xn[e] * nsc[h * 8 + e] + nsh[h * 8 + e];
;                         store_A(Adst, xlayout, r, c8, u); }
;                     else store8f(P->out + (size_t)r * D + c8, xn);
;                 }
;             }
;         }
;         if (nr == 1 && row2 < rend) row -= 8;
.Lrl_X_okA:
	s_waitcnt vmcnt(10)
	v_pk_fma_f32 v[136:137], v[88:89], v[24:25], v[40:41]
	v_pk_fma_f32 v[138:139], v[90:91], v[26:27], v[42:43]
	v_pk_fma_f32 v[140:141], v[92:93], v[28:29], v[44:45]
	v_pk_fma_f32 v[142:143], v[94:95], v[30:31], v[46:47]
	v_pk_fma_f32 v[144:145], v[96:97], v[32:33], v[48:49]
	v_pk_fma_f32 v[146:147], v[98:99], v[34:35], v[50:51]
	v_pk_fma_f32 v[148:149], v[100:101], v[36:37], v[52:53]
	v_pk_fma_f32 v[150:151], v[102:103], v[38:39], v[54:55]
	v_lshlrev_b32_e32 v168, 16, v104
	v_and_b32_e32 v169, s75, v104
	v_lshlrev_b32_e32 v170, 16, v105
	v_and_b32_e32 v171, s75, v105
	v_lshlrev_b32_e32 v172, 16, v106
	v_and_b32_e32 v173, s75, v106
	v_lshlrev_b32_e32 v174, 16, v107
	v_and_b32_e32 v175, s75, v107
	v_lshlrev_b32_e32 v176, 16, v108
	v_and_b32_e32 v177, s75, v108
	v_lshlrev_b32_e32 v178, 16, v109
	v_and_b32_e32 v179, s75, v109
	v_lshlrev_b32_e32 v180, 16, v110
	v_and_b32_e32 v181, s75, v110
	v_lshlrev_b32_e32 v182, 16, v111
	v_and_b32_e32 v183, s75, v111
	s_add_i32 s89, s64, 16
	s_cmp_lt_u32 s89, s46
	s_cselect_b32 s89, s89, s64
	s_lshl_b32 s4, s89, 11
	s_lshl_b32 s5, s89, 12
	s_sub_u32 s6, s5, 0x10000000
	s_cmp_lt_u32 s89, 0x10000
	s_cselect_b32 s5, s5, s6
	s_cselect_b32 s6, s84, s86
	s_cselect_b32 s7, s85, s87
	s_add_u32 s68, s6, s5
	s_addc_u32 s69, s7, 0
	s_add_u32 s66, s76, s4
	s_addc_u32 s67, s77, 0
	global_load_dwordx4 v[88:91], v6, s[68:69]
	global_load_dwordx4 v[92:95], v6, s[68:69] offset:16
	global_load_dwordx4 v[96:99], v6, s[68:69] offset:2048
	global_load_dwordx4 v[100:103], v6, s[68:69] offset:2064
	global_load_dwordx4 v[104:107], v1, s[66:67]
	global_load_dwordx4 v[108:111], v1, s[66:67] offset:1024
	v_pk_fma_f32 v[136:137], v[8:9], v[168:169], v[136:137]
	v_pk_fma_f32 v[138:139], v[10:11], v[170:171], v[138:139]
	v_pk_fma_f32 v[140:141], v[12:13], v[172:173], v[140:141]
	v_pk_fma_f32 v[142:143], v[14:15], v[174:175], v[142:143]
	v_pk_fma_f32 v[144:145], v[16:17], v[176:177], v[144:145]
	v_pk_fma_f32 v[146:147], v[18:19], v[178:179], v[146:147]
	v_pk_fma_f32 v[148:149], v[20:21], v[180:181], v[148:149]
	v_pk_fma_f32 v[150:151], v[22:23], v[182:183], v[150:151]
	v_pk_mul_f32 v[154:155], v[136:137], v[136:137]
	v_pk_add_f32 v[152:153], v[136:137], v[138:139]
	v_pk_fma_f32 v[154:155], v[138:139], v[138:139], v[154:155]
	v_pk_add_f32 v[152:153], v[152:153], v[140:141]
	v_pk_fma_f32 v[154:155], v[140:141], v[140:141], v[154:155]
	v_pk_add_f32 v[152:153], v[152:153], v[142:143]
	v_pk_fma_f32 v[154:155], v[142:143], v[142:143], v[154:155]
	v_pk_add_f32 v[152:153], v[152:153], v[144:145]
	v_pk_fma_f32 v[154:155], v[144:145], v[144:145], v[154:155]
	v_pk_add_f32 v[152:153], v[152:153], v[146:147]
	v_pk_fma_f32 v[154:155], v[146:147], v[146:147], v[154:155]
	v_pk_add_f32 v[152:153], v[152:153], v[148:149]
	v_pk_fma_f32 v[154:155], v[148:149], v[148:149], v[154:155]
	v_pk_add_f32 v[152:153], v[152:153], v[150:151]
	v_pk_fma_f32 v[154:155], v[150:151], v[150:151], v[154:155]
	s_nop 0
	v_add_f32_e32 v156, v152, v153
	v_add_f32_e32 v157, v154, v155
	v_mov_b32_e32 v192, 0
	v_mov_b32_e32 v193, 0
	v_add_f32_dpp v156, v156, v156 row_shr:1 row_mask:0xf bank_mask:0xf bound_ctrl:1
	v_add_f32_dpp v157, v157, v157 row_shr:1 row_mask:0xf bank_mask:0xf bound_ctrl:1
	s_nop 1
	v_add_f32_dpp v156, v156, v156 row_shr:2 row_mask:0xf bank_mask:0xf bound_ctrl:1
	v_add_f32_dpp v157, v157, v157 row_shr:2 row_mask:0xf bank_mask:0xf bound_ctrl:1
	s_nop 1
	v_add_f32_dpp v156, v156, v156 row_shr:4 row_mask:0xf bank_mask:0xf bound_ctrl:1
	v_add_f32_dpp v157, v157, v157 row_shr:4 row_mask:0xf bank_mask:0xf bound_ctrl:1
	s_nop 1
	v_add_f32_dpp v156, v156, v156 row_shr:8 row_mask:0xf bank_mask:0xf bound_ctrl:1
	v_add_f32_dpp v157, v157, v157 row_shr:8 row_mask:0xf bank_mask:0xf bound_ctrl:1
	s_nop 1
	v_mov_b32_dpp v192, v156 row_bcast:15 row_mask:0xa bank_mask:0xf
	v_mov_b32_dpp v193, v157 row_bcast:15 row_mask:0xa bank_mask:0xf
	s_nop 0
	v_add_f32_e32 v156, v156, v192
	v_add_f32_e32 v157, v157, v193
	v_mov_b32_e32 v192, 0
	v_mov_b32_e32 v193, 0
	s_nop 1
	v_mov_b32_dpp v192, v156 row_bcast:31 row_mask:0xc bank_mask:0xf
	v_mov_b32_dpp v193, v157 row_bcast:31 row_mask:0xc bank_mask:0xf
	s_nop 0
	v_add_f32_e32 v156, v156, v192
	v_add_f32_e32 v157, v157, v193
	s_nop 1
	v_readlane_b32 s8, v156, 63
	v_readlane_b32 s9, v157, 63
	s_nop 3
	v_mul_f32_e32 v162, s8, v166
	v_mul_f32_e32 v160, s9, v166
	v_fma_f32 v160, -v162, v162, v160
	v_max_f32_e32 v160, 0, v160
	v_add_f32_e32 v160, 0x3727c5ac, v160
	v_rsq_f32_e32 v158, v160
	s_nop 1
	v_mul_f32_e64 v160, -v162, v158
	s_nop 0
	v_pk_fma_f32 v[136:137], v[136:137], v[158:159], v[160:161] op_sel_hi:[1,0,0]
	v_pk_fma_f32 v[138:139], v[138:139], v[158:159], v[160:161] op_sel_hi:[1,0,0]
	v_pk_fma_f32 v[140:141], v[140:141], v[158:159], v[160:161] op_sel_hi:[1,0,0]
	v_pk_fma_f32 v[142:143], v[142:143], v[158:159], v[160:161] op_sel_hi:[1,0,0]
	v_pk_fma_f32 v[144:145], v[144:145], v[158:159], v[160:161] op_sel_hi:[1,0,0]
	v_pk_fma_f32 v[146:147], v[146:147], v[158:159], v[160:161] op_sel_hi:[1,0,0]
	v_pk_fma_f32 v[148:149], v[148:149], v[158:159], v[160:161] op_sel_hi:[1,0,0]
	v_pk_fma_f32 v[150:151], v[150:151], v[158:159], v[160:161] op_sel_hi:[1,0,0]
	v_pk_fma_f32 v[136:137], v[136:137], v[56:57], v[72:73]
	v_pk_fma_f32 v[138:139], v[138:139], v[58:59], v[74:75]
	v_pk_fma_f32 v[140:141], v[140:141], v[60:61], v[76:77]
	v_pk_fma_f32 v[142:143], v[142:143], v[62:63], v[78:79]
	v_pk_fma_f32 v[144:145], v[144:145], v[64:65], v[80:81]
	v_pk_fma_f32 v[146:147], v[146:147], v[66:67], v[82:83]
	v_pk_fma_f32 v[148:149], v[148:149], v[68:69], v[84:85]
	v_pk_fma_f32 v[150:151], v[150:151], v[70:71], v[86:87]
	s_nop 0
	v_cvt_pk_bf16_f32 v184, v136, v137
	v_cvt_pk_bf16_f32 v185, v138, v139
	v_cvt_pk_bf16_f32 v186, v140, v141
	v_cvt_pk_bf16_f32 v187, v142, v143
	v_cvt_pk_bf16_f32 v188, v144, v145
	v_cvt_pk_bf16_f32 v189, v146, v147
	v_cvt_pk_bf16_f32 v190, v148, v149
	v_cvt_pk_bf16_f32 v191, v150, v151
	s_lshl_b32 s4, s64, 11
	s_add_u32 s68, s62, s4
	s_addc_u32 s69, s63, 0
	global_store_dwordx4 v4, v[184:187], s[68:69]
	global_store_dwordx4 v5, v[188:191], s[68:69]
	s_add_i32 s88, s64, 8
	s_cmp_lt_u32 s88, s46
	s_cbranch_scc0 .Lrl_done
	s_lshr_b32 s4, s88, 11
	s_cmp_eq_u32 s4, s65
	s_cbranch_scc1 .Lrl_X_okB
	s_mov_b32 s91, 1
	s_branch .Lrl_par_X
; __device__ void phase_resid_ln(PP P, int wid, int layer, int sub, const bf16_t* usrc, const bf16_t* msrc, bf16_t* Adst) {
;     ...
;         const int row2 = row + 8;
;         const int nr = (row2 < rend && (row2 >> 11) == seq) ? 2 : 1;
;         float y[2][16], sum[2] = {0.f, 0.f}, sq[2] = {0.f, 0.f};
; #pragma unroll
;         for (int rr = 0; rr < 2; ++rr) {
;             if (rr < nr) {
;                 const int r = row + rr * 8;
; #pragma unroll
;                 for (int h = 0; h < 2; ++h) {
;                     const int c8 = h * 512 + lane * 8; float x[8], m[8];
;                     if (x_from_input) load8f(xin_row(P, r) + c8, x);
;                     else { float u[8]; load_A(usrc, src_xlayout, r, c8, u);
; #pragma unroll
;                         for (int e = 0; e < 8; ++e) x[e] = (u[e] - sh[h * 8 + e]) * sc[h * 8 + e]; }
;                     unpack8(*(const u32x4*)(msrc + (size_t)r * D + c8), m);
; #pragma unroll
;                     for (int e = 0; e < 8; ++e) { const float v = ALPHA * x[e] + gt[h * 8 + e] * m[e]; y[rr][h * 8 + e] = v; sum[rr] += v; sq[rr] += v * v; }
;                 }
;             }
;         }
; #pragma unroll
;         for (int rr = 0; rr < 2; ++rr) {
;             if (rr < nr) {
;                 const int r = row + rr * 8;
;                 const float ts = wave_sum_dpp(sum[rr]), tq = wave_sum_dpp(sq[rr]);
;                 const float mu = ts * (1.f / D), var = fmaxf(tq * (1.f / D) - mu * mu, 0.f), rstd = rsqrtf(var + LN_EPS);
; #pragma unroll
;                 for (int h = 0; h < 2; ++h) {
;                     const int c8 = h * 512 + lane * 8; float xn[8];
; #pragma unroll
;                     for (int e = 0; e < 8; ++e) xn[e] = (y[rr][h * 8 + e] - mu) * rstd * gm[h * 8 + e] + bt[h * 8 + e];
;                     if (has_next) { float u[8];
; #pragma unroll
;                         for (int e = 0; e < 8; ++e) u[e] = xn[e] * nsc[h * 8 + e] + nsh[h * 8 + e];
;                         store_A(Adst, xlayout, r, c8, u); }
;                     else store8f(P->out + (size_t)r * D + c8, xn);
;                 }
;             }
;         }
;         if (nr == 1 && row2 < rend) row -= 8;
.Lrl_X_okB:
	s_waitcnt vmcnt(10)
	v_pk_fma_f32 v[136:137], v[112:113], v[24:25], v[40:41]
	v_pk_fma_f32 v[138:139], v[114:115], v[26:27], v[42:43]
	v_pk_fma_f32 v[140:141], v[116:117], v[28:29], v[44:45]
	v_pk_fma_f32 v[142:143], v[118:119], v[30:31], v[46:47]
	v_pk_fma_f32 v[144:145], v[120:121], v[32:33], v[48:49]
	v_pk_fma_f32 v[146:147], v[122:123], v[34:35], v[50:51]
	v_pk_fma_f32 v[148:149], v[124:125], v[36:37], v[52:53]
	v_pk_fma_f32 v[150:151], v[126:127], v[38:39], v[54:55]
	v_lshlrev_b32_e32 v168, 16, v128
	v_and_b32_e32 v169, s75, v128
	v_lshlrev_b32_e32 v170, 16, v129
	v_and_b32_e32 v171, s75, v129
	v_lshlrev_b32_e32 v172, 16, v130
	v_and_b32_e32 v173, s75, v130
	v_lshlrev_b32_e32 v174, 16, v131
	v_and_b32_e32 v175, s75, v131
	v_lshlrev_b32_e32 v176, 16, v132
	v_and_b32_e32 v177, s75, v132
	v_lshlrev_b32_e32 v178, 16, v133
	v_and_b32_e32 v179, s75, v133
	v_lshlrev_b32_e32 v180, 16, v134
	v_and_b32_e32 v181, s75, v134
	v_lshlrev_b32_e32 v182, 16, v135
	v_and_b32_e32 v183, s75, v135
	s_add_i32 s89, s88, 16
	s_cmp_lt_u32 s89, s46
	s_cselect_b32 s89, s89, s88
	s_lshl_b32 s4, s89, 11
	s_lshl_b32 s5, s89, 12
	s_sub_u32 s6, s5, 0x10000000
	s_cmp_lt_u32 s89, 0x10000
	s_cselect_b32 s5, s5, s6
	s_cselect_b32 s6, s84, s86
	s_cselect_b32 s7, s85, s87
	s_add_u32 s68, s6, s5
	s_addc_u32 s69, s7, 0
	s_add_u32 s66, s76, s4
	s_addc_u32 s67, s77, 0
	global_load_dwordx4 v[112:115], v6, s[68:69]
	global_load_dwordx4 v[116:119], v6, s[68:69] offset:16
	global_load_dwordx4 v[120:123], v6, s[68:69] offset:2048
	global_load_dwordx4 v[124:127], v6, s[68:69] offset:2064
	global_load_dwordx4 v[128:131], v1, s[66:67]
	global_load_dwordx4 v[132:135], v1, s[66:67] offset:1024
	v_pk_fma_f32 v[136:137], v[8:9], v[168:169], v[136:137]
	v_pk_fma_f32 v[138:139], v[10:11], v[170:171], v[138:139]
	v_pk_fma_f32 v[140:141], v[12:13], v[172:173], v[140:141]
	v_pk_fma_f32 v[142:143], v[14:15], v[174:175], v[142:143]
	v_pk_fma_f32 v[144:145], v[16:17], v[176:177], v[144:145]
	v_pk_fma_f32 v[146:147], v[18:19], v[178:179], v[146:147]
	v_pk_fma_f32 v[148:149], v[20:21], v[180:181], v[148:149]
	v_pk_fma_f32 v[150:151], v[22:23], v[182:183], v[150:151]
	v_pk_mul_f32 v[154:155], v[136:137], v[136:137]
	v_pk_add_f32 v[152:153], v[136:137], v[138:139]
	v_pk_fma_f32 v[154:155], v[138:139], v[138:139], v[154:155]
	v_pk_add_f32 v[152:153], v[152:153], v[140:141]
	v_pk_fma_f32 v[154:155], v[140:141], v[140:141], v[154:155]
	v_pk_add_f32 v[152:153], v[152:153], v[142:143]
	v_pk_fma_f32 v[154:155], v[142:143], v[142:143], v[154:155]
	v_pk_add_f32 v[152:153], v[152:153], v[144:145]
	v_pk_fma_f32 v[154:155], v[144:145], v[144:145], v[154:155]
	v_pk_add_f32 v[152:153], v[152:153], v[146:147]
	v_pk_fma_f32 v[154:155], v[146:147], v[146:147], v[154:155]
	v_pk_add_f32 v[152:153], v[152:153], v[148:149]
	v_pk_fma_f32 v[154:155], v[148:149], v[148:149], v[154:155]
	v_pk_add_f32 v[152:153], v[152:153], v[150:151]
	v_pk_fma_f32 v[154:155], v[150:151], v[150:151], v[154:155]
	s_nop 0
	v_add_f32_e32 v156, v152, v153
	v_add_f32_e32 v157, v154, v155
	v_mov_b32_e32 v192, 0
	v_mov_b32_e32 v193, 0
	v_add_f32_dpp v156, v156, v156 row_shr:1 row_mask:0xf bank_mask:0xf bound_ctrl:1
	v_add_f32_dpp v157, v157, v157 row_shr:1 row_mask:0xf bank_mask:0xf bound_ctrl:1
	s_nop 1
	v_add_f32_dpp v156, v156, v156 row_shr:2 row_mask:0xf bank_mask:0xf bound_ctrl:1
	v_add_f32_dpp v157, v157, v157 row_shr:2 row_mask:0xf bank_mask:0xf bound_ctrl:1
	s_nop 1
	v_add_f32_dpp v156, v156, v156 row_shr:4 row_mask:0xf bank_mask:0xf bound_ctrl:1
	v_add_f32_dpp v157, v157, v157 row_shr:4 row_mask:0xf bank_mask:0xf bound_ctrl:1
	s_nop 1
	v_add_f32_dpp v156, v156, v156 row_shr:8 row_mask:0xf bank_mask:0xf bound_ctrl:1
	v_add_f32_dpp v157, v157, v157 row_shr:8 row_mask:0xf bank_mask:0xf bound_ctrl:1
	s_nop 1
	v_mov_b32_dpp v192, v156 row_bcast:15 row_mask:0xa bank_mask:0xf
	v_mov_b32_dpp v193, v157 row_bcast:15 row_mask:0xa bank_mask:0xf
	s_nop 0
	v_add_f32_e32 v156, v156, v192
	v_add_f32_e32 v157, v157, v193
	v_mov_b32_e32 v192, 0
	v_mov_b32_e32 v193, 0
	s_nop 1
	v_mov_b32_dpp v192, v156 row_bcast:31 row_mask:0xc bank_mask:0xf
	v_mov_b32_dpp v193, v157 row_bcast:31 row_mask:0xc bank_mask:0xf
	s_nop 0
	v_add_f32_e32 v156, v156, v192
	v_add_f32_e32 v157, v157, v193
	s_nop 1
	v_readlane_b32 s8, v156, 63
	v_readlane_b32 s9, v157, 63
	s_nop 3
	v_mul_f32_e32 v162, s8, v166
	v_mul_f32_e32 v160, s9, v166
	v_fma_f32 v160, -v162, v162, v160
	v_max_f32_e32 v160, 0, v160
	v_add_f32_e32 v160, 0x3727c5ac, v160
	v_rsq_f32_e32 v158, v160
	s_nop 1
	v_mul_f32_e64 v160, -v162, v158
	s_nop 0
	v_pk_fma_f32 v[136:137], v[136:137], v[158:159], v[160:161] op_sel_hi:[1,0,0]
	v_pk_fma_f32 v[138:139], v[138:139], v[158:159], v[160:161] op_sel_hi:[1,0,0]
	v_pk_fma_f32 v[140:141], v[140:141], v[158:159], v[160:161] op_sel_hi:[1,0,0]
	v_pk_fma_f32 v[142:143], v[142:143], v[158:159], v[160:161] op_sel_hi:[1,0,0]
	v_pk_fma_f32 v[144:145], v[144:145], v[158:159], v[160:161] op_sel_hi:[1,0,0]
	v_pk_fma_f32 v[146:147], v[146:147], v[158:159], v[160:161] op_sel_hi:[1,0,0]
	v_pk_fma_f32 v[148:149], v[148:149], v[158:159], v[160:161] op_sel_hi:[1,0,0]
	v_pk_fma_f32 v[150:151], v[150:151], v[158:159], v[160:161] op_sel_hi:[1,0,0]
	v_pk_fma_f32 v[136:137], v[136:137], v[56:57], v[72:73]
	v_pk_fma_f32 v[138:139], v[138:139], v[58:59], v[74:75]
	v_pk_fma_f32 v[140:141], v[140:141], v[60:61], v[76:77]
	v_pk_fma_f32 v[142:143], v[142:143], v[62:63], v[78:79]
	v_pk_fma_f32 v[144:145], v[144:145], v[64:65], v[80:81]
	v_pk_fma_f32 v[146:147], v[146:147], v[66:67], v[82:83]
	v_pk_fma_f32 v[148:149], v[148:149], v[68:69], v[84:85]
	v_pk_fma_f32 v[150:151], v[150:151], v[70:71], v[86:87]
	s_nop 0
	v_cvt_pk_bf16_f32 v184, v136, v137
	v_cvt_pk_bf16_f32 v185, v138, v139
	v_cvt_pk_bf16_f32 v186, v140, v141
	v_cvt_pk_bf16_f32 v187, v142, v143
	v_cvt_pk_bf16_f32 v188, v144, v145
	v_cvt_pk_bf16_f32 v189, v146, v147
	v_cvt_pk_bf16_f32 v190, v148, v149
	v_cvt_pk_bf16_f32 v191, v150, v151
	s_lshl_b32 s4, s88, 11
	s_add_u32 s68, s62, s4
	s_addc_u32 s69, s63, 0
	global_store_dwordx4 v4, v[184:187], s[68:69]
	global_store_dwordx4 v5, v[188:191], s[68:69]
	s_add_i32 s64, s64, 16
	s_cmp_lt_u32 s64, s46
	s_cbranch_scc1 .Lrl_X_loop
	s_branch .Lrl_done
; __device__ void phase_resid_ln(PP P, int wid, int layer, int sub, const bf16_t* usrc, const bf16_t* msrc, bf16_t* Adst) {
;     ...
;         if (seq != cur_seq) {
;             cur_seq = seq;
;             const float* mrow = mod + (size_t)(layer * NSEQ + seq) * 6 * D;
;             const float* nmrow = mod + (size_t)((has_next ? nl : 0) * NSEQ + seq) * 6 * D;
; #pragma unroll
;             for (int h = 0; h < 2; ++h) { const int c8 = h * 512 + lane * 8; float t[8];
;                 load8f(mrow + (sub == 0 ? 2 : 5) * D + c8, t);
; #pragma unroll
;                 for (int e = 0; e < 8; ++e) gt[h * 8 + e] = 1.f + t[e];
;                 load8f(mrow + (sub == 0 ? 0 : 3) * D + c8, t);
; #pragma unroll
;                 for (int e = 0; e < 8; ++e) sh[h * 8 + e] = t[e];
;                 load8f(mrow + (sub == 0 ? 1 : 4) * D + c8, t);
; #pragma unroll
;                 for (int e = 0; e < 8; ++e) sc[h * 8 + e] = __builtin_amdgcn_rcpf(1.f + t[e]);
;                 load8f(nmrow + (nsub == 0 ? 0 : 3) * D + c8, t);
; #pragma unroll
;                 for (int e = 0; e < 8; ++e) nsh[h * 8 + e] = t[e];
;                 load8f(nmrow + (nsub == 0 ? 1 : 4) * D + c8, t);
; #pragma unroll
;                 for (int e = 0; e < 8; ++e) nsc[h * 8 + e] = 1.f + t[e]; }
;         }
.Lrl_par_X:
	s_mov_b32 s65, s4
	s_mul_i32 s5, s4, 0x6000
	s_add_u32 s10, s70, s5
	s_addc_u32 s11, s71, 0
	s_add_u32 s10, s10, 0x2000
	s_addc_u32 s11, s11, 0
	global_load_dwordx4 v[8:11], v6, s[10:11]
	global_load_dwordx4 v[12:15], v6, s[10:11] offset:16
	global_load_dwordx4 v[16:19], v6, s[10:11] offset:2048
	global_load_dwordx4 v[20:23], v6, s[10:11] offset:2064
	s_add_i32 s5, s25, s72
	s_mul_i32 s5, s5, 40
	s_add_i32 s5, s5, s4
	s_mul_i32 s5, s5, 0x6000
	s_xor_b32 s6, s72, 1
	s_mul_i32 s6, s6, 0x3000
	s_add_i32 s5, s5, s6
	s_add_u32 s6, s70, s5
	s_addc_u32 s7, s71, 0
	s_add_u32 s8, s6, 0x1000
	s_addc_u32 s9, s7, 0
	global_load_dwordx4 v[72:75], v6, s[6:7]
	global_load_dwordx4 v[76:79], v6, s[6:7] offset:16
	global_load_dwordx4 v[80:83], v6, s[6:7] offset:2048
	global_load_dwordx4 v[84:87], v6, s[6:7] offset:2064
	global_load_dwordx4 v[56:59], v6, s[8:9]
	global_load_dwordx4 v[60:63], v6, s[8:9] offset:16
	global_load_dwordx4 v[64:67], v6, s[8:9] offset:2048
	global_load_dwordx4 v[68:71], v6, s[8:9] offset:2064
	global_load_dwordx4 v[168:171], v6, s[80:81]
	global_load_dwordx4 v[172:175], v6, s[80:81] offset:16
	global_load_dwordx4 v[176:179], v6, s[80:81] offset:2048
	global_load_dwordx4 v[180:183], v6, s[80:81] offset:2064
	global_load_dwordx4 v[136:139], v6, s[82:83]
	global_load_dwordx4 v[140:143], v6, s[82:83] offset:16
	global_load_dwordx4 v[144:147], v6, s[82:83] offset:2048
	global_load_dwordx4 v[148:151], v6, s[82:83] offset:2064
	s_waitcnt vmcnt(0)
	v_pk_add_f32 v[8:9], v[8:9], 1.0 op_sel_hi:[1,0]
	v_pk_add_f32 v[10:11], v[10:11], 1.0 op_sel_hi:[1,0]
	v_pk_add_f32 v[12:13], v[12:13], 1.0 op_sel_hi:[1,0]
	v_pk_add_f32 v[14:15], v[14:15], 1.0 op_sel_hi:[1,0]
	v_pk_add_f32 v[16:17], v[16:17], 1.0 op_sel_hi:[1,0]
	v_pk_add_f32 v[18:19], v[18:19], 1.0 op_sel_hi:[1,0]
	v_pk_add_f32 v[20:21], v[20:21], 1.0 op_sel_hi:[1,0]
	v_pk_add_f32 v[22:23], v[22:23], 1.0 op_sel_hi:[1,0]
	v_mov_b32_e32 v24, s36
	v_mov_b32_e32 v25, s36
	v_mov_b32_e32 v26, s36
	v_mov_b32_e32 v27, s36
	v_mov_b32_e32 v28, s36
	v_mov_b32_e32 v29, s36
	v_mov_b32_e32 v30, s36
	v_mov_b32_e32 v31, s36
	v_mov_b32_e32 v32, s36
	v_mov_b32_e32 v33, s36
	v_mov_b32_e32 v34, s36
	v_mov_b32_e32 v35, s36
	v_mov_b32_e32 v36, s36
	v_mov_b32_e32 v37, s36
	v_mov_b32_e32 v38, s36
	v_mov_b32_e32 v39, s36
	v_mov_b32_e32 v40, 0
	v_mov_b32_e32 v41, 0
	v_mov_b32_e32 v42, 0
	v_mov_b32_e32 v43, 0
	v_mov_b32_e32 v44, 0
	v_mov_b32_e32 v45, 0
	v_mov_b32_e32 v46, 0
	v_mov_b32_e32 v47, 0
	v_mov_b32_e32 v48, 0
	v_mov_b32_e32 v49, 0
	v_mov_b32_e32 v50, 0
	v_mov_b32_e32 v51, 0
	v_mov_b32_e32 v52, 0
	v_mov_b32_e32 v53, 0
	v_mov_b32_e32 v54, 0
	v_mov_b32_e32 v55, 0
	v_pk_add_f32 v[56:57], v[56:57], 1.0 op_sel_hi:[1,0]
	v_pk_add_f32 v[58:59], v[58:59], 1.0 op_sel_hi:[1,0]
	v_pk_add_f32 v[60:61], v[60:61], 1.0 op_sel_hi:[1,0]
	v_pk_add_f32 v[62:63], v[62:63], 1.0 op_sel_hi:[1,0]
	v_pk_add_f32 v[64:65], v[64:65], 1.0 op_sel_hi:[1,0]
	v_pk_add_f32 v[66:67], v[66:67], 1.0 op_sel_hi:[1,0]
	v_pk_add_f32 v[68:69], v[68:69], 1.0 op_sel_hi:[1,0]
	v_pk_add_f32 v[70:71], v[70:71], 1.0 op_sel_hi:[1,0]
	v_pk_fma_f32 v[72:73], v[136:137], v[56:57], v[72:73]
	v_pk_fma_f32 v[74:75], v[138:139], v[58:59], v[74:75]
	v_pk_fma_f32 v[76:77], v[140:141], v[60:61], v[76:77]
	v_pk_fma_f32 v[78:79], v[142:143], v[62:63], v[78:79]
	v_pk_fma_f32 v[80:81], v[144:145], v[64:65], v[80:81]
	v_pk_fma_f32 v[82:83], v[146:147], v[66:67], v[82:83]
	v_pk_fma_f32 v[84:85], v[148:149], v[68:69], v[84:85]
	v_pk_fma_f32 v[86:87], v[150:151], v[70:71], v[86:87]
	v_pk_mul_f32 v[56:57], v[56:57], v[168:169]
	v_pk_mul_f32 v[58:59], v[58:59], v[170:171]
	v_pk_mul_f32 v[60:61], v[60:61], v[172:173]
	v_pk_mul_f32 v[62:63], v[62:63], v[174:175]
	v_pk_mul_f32 v[64:65], v[64:65], v[176:177]
	v_pk_mul_f32 v[66:67], v[66:67], v[178:179]
	v_pk_mul_f32 v[68:69], v[68:69], v[180:181]
	v_pk_mul_f32 v[70:71], v[70:71], v[182:183]
	s_nop 1
	s_cmp_eq_u32 s91, 0
	s_cbranch_scc1 .Lrl_X_okA
	s_branch .Lrl_X_okB
.Lrl_F_start:
	s_lshl_b32 s4, s64, 11
	s_add_u32 s68, s60, s4
	s_addc_u32 s69, s61, 0
	s_add_u32 s66, s76, s4
	s_addc_u32 s67, s77, 0
	global_load_dwordx4 v[88:91], v2, s[68:69]
	global_load_dwordx4 v[92:95], v3, s[68:69]
	global_load_dwordx4 v[104:107], v1, s[66:67]
	global_load_dwordx4 v[108:111], v1, s[66:67] offset:1024
	s_add_i32 s88, s64, 8
	s_cmp_lt_u32 s88, s46
	s_cselect_b32 s89, s88, s64
	s_lshl_b32 s4, s89, 11
	s_add_u32 s68, s60, s4
	s_addc_u32 s69, s61, 0
	s_add_u32 s66, s76, s4
	s_addc_u32 s67, s77, 0
	global_load_dwordx4 v[112:115], v2, s[68:69]
	global_load_dwordx4 v[116:119], v3, s[68:69]
	global_load_dwordx4 v[128:131], v1, s[66:67]
	global_load_dwordx4 v[132:135], v1, s[66:67] offset:1024

; __device__ void phase_resid_ln(PP P, int wid, int layer, int sub, const bf16_t* usrc, const bf16_t* msrc, bf16_t* Adst) {
;     ...
;         const int row2 = row + 8;
;         const int nr = (row2 < rend && (row2 >> 11) == seq) ? 2 : 1;
;         float y[2][16], sum[2] = {0.f, 0.f}, sq[2] = {0.f, 0.f};
; #pragma unroll
;         for (int rr = 0; rr < 2; ++rr) {
;             if (rr < nr) {
;                 const int r = row + rr * 8;
; #pragma unroll
;                 for (int h = 0; h < 2; ++h) {
;                     const int c8 = h * 512 + lane * 8; float x[8], m[8];
;                     if (x_from_input) load8f(xin_row(P, r) + c8, x);
;                     else { float u[8]; load_A(usrc, src_xlayout, r, c8, u);
; #pragma unroll
;                         for (int e = 0; e < 8; ++e) x[e] = (u[e] - sh[h * 8 + e]) * sc[h * 8 + e]; }
;                     unpack8(*(const u32x4*)(msrc + (size_t)r * D + c8), m);
; #pragma unroll
;                     for (int e = 0; e < 8; ++e) { const float v = ALPHA * x[e] + gt[h * 8 + e] * m[e]; y[rr][h * 8 + e] = v; sum[rr] += v; sq[rr] += v * v; }
;                 }
;             }
;         }
; #pragma unroll
;         for (int rr = 0; rr < 2; ++rr) {
;             if (rr < nr) {
;                 const int r = row + rr * 8;
;                 const float ts = wave_sum_dpp(sum[rr]), tq = wave_sum_dpp(sq[rr]);
;                 const float mu = ts * (1.f / D), var = fmaxf(tq * (1.f / D) - mu * mu, 0.f), rstd = rsqrtf(var + LN_EPS);
; #pragma unroll
;                 for (int h = 0; h < 2; ++h) {
;                     const int c8 = h * 512 + lane * 8; float xn[8];
; #pragma unroll
;                     for (int e = 0; e < 8; ++e) xn[e] = (y[rr][h * 8 + e] - mu) * rstd * gm[h * 8 + e] + bt[h * 8 + e];
;                     if (has_next) { float u[8];
; #pragma unroll
;                         for (int e = 0; e < 8; ++e) u[e] = xn[e] * nsc[h * 8 + e] + nsh[h * 8 + e];
;                         store_A(Adst, xlayout, r, c8, u); }
;                     else store8f(P->out + (size_t)r * D + c8, xn);
;                 }
;             }
;         }
;         if (nr == 1 && row2 < rend) row -= 8;
.Lrl_F_okA:
	s_waitcnt vmcnt(12)
	v_lshlrev_b32_e32 v168, 16, v88
	v_and_b32_e32 v169, s75, v88
	v_lshlrev_b32_e32 v170, 16, v89
	v_and_b32_e32 v171, s75, v89
	v_lshlrev_b32_e32 v172, 16, v90
	v_and_b32_e32 v173, s75, v90
	v_lshlrev_b32_e32 v174, 16, v91
	v_and_b32_e32 v175, s75, v91
	v_lshlrev_b32_e32 v176, 16, v92
	v_and_b32_e32 v177, s75, v92
	v_lshlrev_b32_e32 v178, 16, v93
	v_and_b32_e32 v179, s75, v93
	v_lshlrev_b32_e32 v180, 16, v94
	v_and_b32_e32 v181, s75, v94
	v_lshlrev_b32_e32 v182, 16, v95
	v_and_b32_e32 v183, s75, v95
	v_pk_fma_f32 v[136:137], v[168:169], v[24:25], v[40:41]
	v_pk_fma_f32 v[138:139], v[170:171], v[26:27], v[42:43]
	v_pk_fma_f32 v[140:141], v[172:173], v[28:29], v[44:45]
	v_pk_fma_f32 v[142:143], v[174:175], v[30:31], v[46:47]
	v_pk_fma_f32 v[144:145], v[176:177], v[32:33], v[48:49]
	v_pk_fma_f32 v[146:147], v[178:179], v[34:35], v[50:51]
	v_pk_fma_f32 v[148:149], v[180:181], v[36:37], v[52:53]
	v_pk_fma_f32 v[150:151], v[182:183], v[38:39], v[54:55]
	v_lshlrev_b32_e32 v168, 16, v104
	v_and_b32_e32 v169, s75, v104
	v_lshlrev_b32_e32 v170, 16, v105
	v_and_b32_e32 v171, s75, v105
	v_lshlrev_b32_e32 v172, 16, v106
	v_and_b32_e32 v173, s75, v106
	v_lshlrev_b32_e32 v174, 16, v107
	v_and_b32_e32 v175, s75, v107
	v_lshlrev_b32_e32 v176, 16, v108
	v_and_b32_e32 v177, s75, v108
	v_lshlrev_b32_e32 v178, 16, v109
	v_and_b32_e32 v179, s75, v109
	v_lshlrev_b32_e32 v180, 16, v110
	v_and_b32_e32 v181, s75, v110
	v_lshlrev_b32_e32 v182, 16, v111
	v_and_b32_e32 v183, s75, v111
	s_add_i32 s89, s64, 16
	s_cmp_lt_u32 s89, s46
	s_cselect_b32 s89, s89, s64
	s_lshl_b32 s4, s89, 11
	s_add_u32 s68, s60, s4
	s_addc_u32 s69, s61, 0
	s_add_u32 s66, s76, s4
	s_addc_u32 s67, s77, 0
	global_load_dwordx4 v[88:91], v2, s[68:69]
	global_load_dwordx4 v[92:95], v3, s[68:69]
	global_load_dwordx4 v[104:107], v1, s[66:67]
	global_load_dwordx4 v[108:111], v1, s[66:67] offset:1024
	v_pk_fma_f32 v[136:137], v[8:9], v[168:169], v[136:137]
	v_pk_fma_f32 v[138:139], v[10:11], v[170:171], v[138:139]
	v_pk_fma_f32 v[140:141], v[12:13], v[172:173], v[140:141]
	v_pk_fma_f32 v[142:143], v[14:15], v[174:175], v[142:143]
	v_pk_fma_f32 v[144:145], v[16:17], v[176:177], v[144:145]
	v_pk_fma_f32 v[146:147], v[18:19], v[178:179], v[146:147]
	v_pk_fma_f32 v[148:149], v[20:21], v[180:181], v[148:149]
	v_pk_fma_f32 v[150:151], v[22:23], v[182:183], v[150:151]
	v_pk_mul_f32 v[154:155], v[136:137], v[136:137]
	v_pk_add_f32 v[152:153], v[136:137], v[138:139]
	v_pk_fma_f32 v[154:155], v[138:139], v[138:139], v[154:155]
	v_pk_add_f32 v[152:153], v[152:153], v[140:141]
	v_pk_fma_f32 v[154:155], v[140:141], v[140:141], v[154:155]
	v_pk_add_f32 v[152:153], v[152:153], v[142:143]
	v_pk_fma_f32 v[154:155], v[142:143], v[142:143], v[154:155]
	v_pk_add_f32 v[152:153], v[152:153], v[144:145]
	v_pk_fma_f32 v[154:155], v[144:145], v[144:145], v[154:155]
	v_pk_add_f32 v[152:153], v[152:153], v[146:147]
	v_pk_fma_f32 v[154:155], v[146:147], v[146:147], v[154:155]
	v_pk_add_f32 v[152:153], v[152:153], v[148:149]
	v_pk_fma_f32 v[154:155], v[148:149], v[148:149], v[154:155]
	v_pk_add_f32 v[152:153], v[152:153], v[150:151]
	v_pk_fma_f32 v[154:155], v[150:151], v[150:151], v[154:155]
	s_nop 0
	v_add_f32_e32 v156, v152, v153
	v_add_f32_e32 v157, v154, v155
	v_mov_b32_e32 v192, 0
	v_mov_b32_e32 v193, 0
	v_add_f32_dpp v156, v156, v156 row_shr:1 row_mask:0xf bank_mask:0xf bound_ctrl:1
	v_add_f32_dpp v157, v157, v157 row_shr:1 row_mask:0xf bank_mask:0xf bound_ctrl:1
	s_nop 1
	v_add_f32_dpp v156, v156, v156 row_shr:2 row_mask:0xf bank_mask:0xf bound_ctrl:1
	v_add_f32_dpp v157, v157, v157 row_shr:2 row_mask:0xf bank_mask:0xf bound_ctrl:1
	s_nop 1
	v_add_f32_dpp v156, v156, v156 row_shr:4 row_mask:0xf bank_mask:0xf bound_ctrl:1
	v_add_f32_dpp v157, v157, v157 row_shr:4 row_mask:0xf bank_mask:0xf bound_ctrl:1
	s_nop 1
	v_add_f32_dpp v156, v156, v156 row_shr:8 row_mask:0xf bank_mask:0xf bound_ctrl:1
	v_add_f32_dpp v157, v157, v157 row_shr:8 row_mask:0xf bank_mask:0xf bound_ctrl:1
	s_nop 1
	v_mov_b32_dpp v192, v156 row_bcast:15 row_mask:0xa bank_mask:0xf
	v_mov_b32_dpp v193, v157 row_bcast:15 row_mask:0xa bank_mask:0xf
	s_nop 0
	v_add_f32_e32 v156, v156, v192
	v_add_f32_e32 v157, v157, v193
	v_mov_b32_e32 v192, 0
	v_mov_b32_e32 v193, 0
	s_nop 1
	v_mov_b32_dpp v192, v156 row_bcast:31 row_mask:0xc bank_mask:0xf
	v_mov_b32_dpp v193, v157 row_bcast:31 row_mask:0xc bank_mask:0xf
	s_nop 0
	v_add_f32_e32 v156, v156, v192
	v_add_f32_e32 v157, v157, v193
	s_nop 1
	v_readlane_b32 s8, v156, 63
	v_readlane_b32 s9, v157, 63
	s_nop 3
	v_mul_f32_e32 v162, s8, v166
	v_mul_f32_e32 v160, s9, v166
	v_fma_f32 v160, -v162, v162, v160
	v_max_f32_e32 v160, 0, v160
	v_add_f32_e32 v160, 0x3727c5ac, v160
	v_rsq_f32_e32 v158, v160
	s_nop 1
	v_mul_f32_e64 v160, -v162, v158
	s_nop 0
	v_pk_fma_f32 v[136:137], v[136:137], v[158:159], v[160:161] op_sel_hi:[1,0,0]
	v_pk_fma_f32 v[138:139], v[138:139], v[158:159], v[160:161] op_sel_hi:[1,0,0]
	v_pk_fma_f32 v[140:141], v[140:141], v[158:159], v[160:161] op_sel_hi:[1,0,0]
	v_pk_fma_f32 v[142:143], v[142:143], v[158:159], v[160:161] op_sel_hi:[1,0,0]
	v_pk_fma_f32 v[144:145], v[144:145], v[158:159], v[160:161] op_sel_hi:[1,0,0]
	v_pk_fma_f32 v[146:147], v[146:147], v[158:159], v[160:161] op_sel_hi:[1,0,0]
	v_pk_fma_f32 v[148:149], v[148:149], v[158:159], v[160:161] op_sel_hi:[1,0,0]
	v_pk_fma_f32 v[150:151], v[150:151], v[158:159], v[160:161] op_sel_hi:[1,0,0]
	v_pk_fma_f32 v[136:137], v[136:137], v[56:57], v[72:73]
	v_pk_fma_f32 v[138:139], v[138:139], v[58:59], v[74:75]
	v_pk_fma_f32 v[140:141], v[140:141], v[60:61], v[76:77]
	v_pk_fma_f32 v[142:143], v[142:143], v[62:63], v[78:79]
	v_pk_fma_f32 v[144:145], v[144:145], v[64:65], v[80:81]
	v_pk_fma_f32 v[146:147], v[146:147], v[66:67], v[82:83]
	v_pk_fma_f32 v[148:149], v[148:149], v[68:69], v[84:85]
	v_pk_fma_f32 v[150:151], v[150:151], v[70:71], v[86:87]
	s_lshl_b32 s4, s64, 12
	s_add_u32 s68, s84, s4
	s_addc_u32 s69, s85, 0
	s_nop 0
	global_store_dwordx4 v6, v[136:139], s[68:69]
	global_store_dwordx4 v6, v[140:143], s[68:69] offset:16
	global_store_dwordx4 v6, v[144:147], s[68:69] offset:2048
	global_store_dwordx4 v6, v[148:151], s[68:69] offset:2064
	s_add_i32 s88, s64, 8
	s_cmp_lt_u32 s88, s46
	s_cbranch_scc0 .Lrl_done
	s_lshr_b32 s4, s88, 11
	s_cmp_eq_u32 s4, s65
	s_cbranch_scc1 .Lrl_F_okB
	s_mov_b32 s91, 1
	s_branch .Lrl_par_F
; __device__ void phase_resid_ln(PP P, int wid, int layer, int sub, const bf16_t* usrc, const bf16_t* msrc, bf16_t* Adst) {
;     ...
;         const int row2 = row + 8;
;         const int nr = (row2 < rend && (row2 >> 11) == seq) ? 2 : 1;
;         float y[2][16], sum[2] = {0.f, 0.f}, sq[2] = {0.f, 0.f};
; #pragma unroll
;         for (int rr = 0; rr < 2; ++rr) {
;             if (rr < nr) {
;                 const int r = row + rr * 8;
; #pragma unroll
;                 for (int h = 0; h < 2; ++h) {
;                     const int c8 = h * 512 + lane * 8; float x[8], m[8];
;                     if (x_from_input) load8f(xin_row(P, r) + c8, x);
;                     else { float u[8]; load_A(usrc, src_xlayout, r, c8, u);
; #pragma unroll
;                         for (int e = 0; e < 8; ++e) x[e] = (u[e] - sh[h * 8 + e]) * sc[h * 8 + e]; }
;                     unpack8(*(const u32x4*)(msrc + (size_t)r * D + c8), m);
; #pragma unroll
;                     for (int e = 0; e < 8; ++e) { const float v = ALPHA * x[e] + gt[h * 8 + e] * m[e]; y[rr][h * 8 + e] = v; sum[rr] += v; sq[rr] += v * v; }
;                 }
;             }
;         }
; #pragma unroll
;         for (int rr = 0; rr < 2; ++rr) {
;             if (rr < nr) {
;                 const int r = row + rr * 8;
;                 const float ts = wave_sum_dpp(sum[rr]), tq = wave_sum_dpp(sq[rr]);
;                 const float mu = ts * (1.f / D), var = fmaxf(tq * (1.f / D) - mu * mu, 0.f), rstd = rsqrtf(var + LN_EPS);
; #pragma unroll
;                 for (int h = 0; h < 2; ++h) {
;                     const int c8 = h * 512 + lane * 8; float xn[8];
; #pragma unroll
;                     for (int e = 0; e < 8; ++e) xn[e] = (y[rr][h * 8 + e] - mu) * rstd * gm[h * 8 + e] + bt[h * 8 + e];
;                     if (has_next) { float u[8];
; #pragma unroll
;                         for (int e = 0; e < 8; ++e) u[e] = xn[e] * nsc[h * 8 + e] + nsh[h * 8 + e];
;                         store_A(Adst, xlayout, r, c8, u); }
;                     else store8f(P->out + (size_t)r * D + c8, xn);
;                 }
;             }
;         }
;         if (nr == 1 && row2 < rend) row -= 8;
.Lrl_F_okB:
	s_waitcnt vmcnt(12)
	v_lshlrev_b32_e32 v168, 16, v112
	v_and_b32_e32 v169, s75, v112
	v_lshlrev_b32_e32 v170, 16, v113
	v_and_b32_e32 v171, s75, v113
	v_lshlrev_b32_e32 v172, 16, v114
	v_and_b32_e32 v173, s75, v114
	v_lshlrev_b32_e32 v174, 16, v115
	v_and_b32_e32 v175, s75, v115
	v_lshlrev_b32_e32 v176, 16, v116
	v_and_b32_e32 v177, s75, v116
	v_lshlrev_b32_e32 v178, 16, v117
	v_and_b32_e32 v179, s75, v117
	v_lshlrev_b32_e32 v180, 16, v118
	v_and_b32_e32 v181, s75, v118
	v_lshlrev_b32_e32 v182, 16, v119
	v_and_b32_e32 v183, s75, v119
	v_pk_fma_f32 v[136:137], v[168:169], v[24:25], v[40:41]
	v_pk_fma_f32 v[138:139], v[170:171], v[26:27], v[42:43]
	v_pk_fma_f32 v[140:141], v[172:173], v[28:29], v[44:45]
	v_pk_fma_f32 v[142:143], v[174:175], v[30:31], v[46:47]
	v_pk_fma_f32 v[144:145], v[176:177], v[32:33], v[48:49]
	v_pk_fma_f32 v[146:147], v[178:179], v[34:35], v[50:51]
	v_pk_fma_f32 v[148:149], v[180:181], v[36:37], v[52:53]
	v_pk_fma_f32 v[150:151], v[182:183], v[38:39], v[54:55]
	v_lshlrev_b32_e32 v168, 16, v128
	v_and_b32_e32 v169, s75, v128
	v_lshlrev_b32_e32 v170, 16, v129
	v_and_b32_e32 v171, s75, v129
	v_lshlrev_b32_e32 v172, 16, v130
	v_and_b32_e32 v173, s75, v130
	v_lshlrev_b32_e32 v174, 16, v131
	v_and_b32_e32 v175, s75, v131
	v_lshlrev_b32_e32 v176, 16, v132
	v_and_b32_e32 v177, s75, v132
	v_lshlrev_b32_e32 v178, 16, v133
	v_and_b32_e32 v179, s75, v133
	v_lshlrev_b32_e32 v180, 16, v134
	v_and_b32_e32 v181, s75, v134
	v_lshlrev_b32_e32 v182, 16, v135
	v_and_b32_e32 v183, s75, v135
	s_add_i32 s89, s88, 16
	s_cmp_lt_u32 s89, s46
	s_cselect_b32 s89, s89, s88
	s_lshl_b32 s4, s89, 11
	s_add_u32 s68, s60, s4
	s_addc_u32 s69, s61, 0
	s_add_u32 s66, s76, s4
	s_addc_u32 s67, s77, 0
	global_load_dwordx4 v[112:115], v2, s[68:69]
	global_load_dwordx4 v[116:119], v3, s[68:69]
	global_load_dwordx4 v[128:131], v1, s[66:67]
	global_load_dwordx4 v[132:135], v1, s[66:67] offset:1024
	v_pk_fma_f32 v[136:137], v[8:9], v[168:169], v[136:137]
	v_pk_fma_f32 v[138:139], v[10:11], v[170:171], v[138:139]
	v_pk_fma_f32 v[140:141], v[12:13], v[172:173], v[140:141]
	v_pk_fma_f32 v[142:143], v[14:15], v[174:175], v[142:143]
	v_pk_fma_f32 v[144:145], v[16:17], v[176:177], v[144:145]
	v_pk_fma_f32 v[146:147], v[18:19], v[178:179], v[146:147]
	v_pk_fma_f32 v[148:149], v[20:21], v[180:181], v[148:149]
	v_pk_fma_f32 v[150:151], v[22:23], v[182:183], v[150:151]
	v_pk_mul_f32 v[154:155], v[136:137], v[136:137]
	v_pk_add_f32 v[152:153], v[136:137], v[138:139]
	v_pk_fma_f32 v[154:155], v[138:139], v[138:139], v[154:155]
	v_pk_add_f32 v[152:153], v[152:153], v[140:141]
	v_pk_fma_f32 v[154:155], v[140:141], v[140:141], v[154:155]
	v_pk_add_f32 v[152:153], v[152:153], v[142:143]
	v_pk_fma_f32 v[154:155], v[142:143], v[142:143], v[154:155]
	v_pk_add_f32 v[152:153], v[152:153], v[144:145]
	v_pk_fma_f32 v[154:155], v[144:145], v[144:145], v[154:155]
	v_pk_add_f32 v[152:153], v[152:153], v[146:147]
	v_pk_fma_f32 v[154:155], v[146:147], v[146:147], v[154:155]
	v_pk_add_f32 v[152:153], v[152:153], v[148:149]
	v_pk_fma_f32 v[154:155], v[148:149], v[148:149], v[154:155]
	v_pk_add_f32 v[152:153], v[152:153], v[150:151]
	v_pk_fma_f32 v[154:155], v[150:151], v[150:151], v[154:155]
	s_nop 0
	v_add_f32_e32 v156, v152, v153
	v_add_f32_e32 v157, v154, v155
	v_mov_b32_e32 v192, 0
	v_mov_b32_e32 v193, 0
	v_add_f32_dpp v156, v156, v156 row_shr:1 row_mask:0xf bank_mask:0xf bound_ctrl:1
	v_add_f32_dpp v157, v157, v157 row_shr:1 row_mask:0xf bank_mask:0xf bound_ctrl:1
	s_nop 1
	v_add_f32_dpp v156, v156, v156 row_shr:2 row_mask:0xf bank_mask:0xf bound_ctrl:1
	v_add_f32_dpp v157, v157, v157 row_shr:2 row_mask:0xf bank_mask:0xf bound_ctrl:1
	s_nop 1
	v_add_f32_dpp v156, v156, v156 row_shr:4 row_mask:0xf bank_mask:0xf bound_ctrl:1
	v_add_f32_dpp v157, v157, v157 row_shr:4 row_mask:0xf bank_mask:0xf bound_ctrl:1
	s_nop 1
	v_add_f32_dpp v156, v156, v156 row_shr:8 row_mask:0xf bank_mask:0xf bound_ctrl:1
	v_add_f32_dpp v157, v157, v157 row_shr:8 row_mask:0xf bank_mask:0xf bound_ctrl:1
	s_nop 1
	v_mov_b32_dpp v192, v156 row_bcast:15 row_mask:0xa bank_mask:0xf
	v_mov_b32_dpp v193, v157 row_bcast:15 row_mask:0xa bank_mask:0xf
	s_nop 0
	v_add_f32_e32 v156, v156, v192
	v_add_f32_e32 v157, v157, v193
	v_mov_b32_e32 v192, 0
	v_mov_b32_e32 v193, 0
	s_nop 1
	v_mov_b32_dpp v192, v156 row_bcast:31 row_mask:0xc bank_mask:0xf
	v_mov_b32_dpp v193, v157 row_bcast:31 row_mask:0xc bank_mask:0xf
	s_nop 0
	v_add_f32_e32 v156, v156, v192
	v_add_f32_e32 v157, v157, v193
	s_nop 1
	v_readlane_b32 s8, v156, 63
	v_readlane_b32 s9, v157, 63
	s_nop 3
	v_mul_f32_e32 v162, s8, v166
	v_mul_f32_e32 v160, s9, v166
	v_fma_f32 v160, -v162, v162, v160
	v_max_f32_e32 v160, 0, v160
	v_add_f32_e32 v160, 0x3727c5ac, v160
	v_rsq_f32_e32 v158, v160
	s_nop 1
	v_mul_f32_e64 v160, -v162, v158
	s_nop 0
	v_pk_fma_f32 v[136:137], v[136:137], v[158:159], v[160:161] op_sel_hi:[1,0,0]
	v_pk_fma_f32 v[138:139], v[138:139], v[158:159], v[160:161] op_sel_hi:[1,0,0]
	v_pk_fma_f32 v[140:141], v[140:141], v[158:159], v[160:161] op_sel_hi:[1,0,0]
	v_pk_fma_f32 v[142:143], v[142:143], v[158:159], v[160:161] op_sel_hi:[1,0,0]
	v_pk_fma_f32 v[144:145], v[144:145], v[158:159], v[160:161] op_sel_hi:[1,0,0]
	v_pk_fma_f32 v[146:147], v[146:147], v[158:159], v[160:161] op_sel_hi:[1,0,0]
	v_pk_fma_f32 v[148:149], v[148:149], v[158:159], v[160:161] op_sel_hi:[1,0,0]
	v_pk_fma_f32 v[150:151], v[150:151], v[158:159], v[160:161] op_sel_hi:[1,0,0]
	v_pk_fma_f32 v[136:137], v[136:137], v[56:57], v[72:73]
	v_pk_fma_f32 v[138:139], v[138:139], v[58:59], v[74:75]
	v_pk_fma_f32 v[140:141], v[140:141], v[60:61], v[76:77]
	v_pk_fma_f32 v[142:143], v[142:143], v[62:63], v[78:79]
	v_pk_fma_f32 v[144:145], v[144:145], v[64:65], v[80:81]
	v_pk_fma_f32 v[146:147], v[146:147], v[66:67], v[82:83]
	v_pk_fma_f32 v[148:149], v[148:149], v[68:69], v[84:85]
	v_pk_fma_f32 v[150:151], v[150:151], v[70:71], v[86:87]
	s_lshl_b32 s4, s88, 12
	s_add_u32 s68, s84, s4
	s_addc_u32 s69, s85, 0
	s_nop 0
	global_store_dwordx4 v6, v[136:139], s[68:69]
	global_store_dwordx4 v6, v[140:143], s[68:69] offset:16
	global_store_dwordx4 v6, v[144:147], s[68:69] offset:2048
	global_store_dwordx4 v6, v[148:151], s[68:69] offset:2064
	s_add_i32 s64, s64, 16
	s_cmp_lt_u32 s64, s46
	s_cbranch_scc1 .Lrl_F_loop
	s_branch .Lrl_done
; __device__ void phase_resid_ln(PP P, int wid, int layer, int sub, const bf16_t* usrc, const bf16_t* msrc, bf16_t* Adst) {
;     ...
;         if (seq != cur_seq) {
;             cur_seq = seq;
;             const float* mrow = mod + (size_t)(layer * NSEQ + seq) * 6 * D;
;             const float* nmrow = mod + (size_t)((has_next ? nl : 0) * NSEQ + seq) * 6 * D;
; #pragma unroll
;             for (int h = 0; h < 2; ++h) { const int c8 = h * 512 + lane * 8; float t[8];
;                 load8f(mrow + (sub == 0 ? 2 : 5) * D + c8, t);
; #pragma unroll
;                 for (int e = 0; e < 8; ++e) gt[h * 8 + e] = 1.f + t[e];
;                 load8f(mrow + (sub == 0 ? 0 : 3) * D + c8, t);
; #pragma unroll
;                 for (int e = 0; e < 8; ++e) sh[h * 8 + e] = t[e];
;                 load8f(mrow + (sub == 0 ? 1 : 4) * D + c8, t);
; #pragma unroll
;                 for (int e = 0; e < 8; ++e) sc[h * 8 + e] = __builtin_amdgcn_rcpf(1.f + t[e]);
;                 load8f(nmrow + (nsub == 0 ? 0 : 3) * D + c8, t);
; #pragma unroll
;                 for (int e = 0; e < 8; ++e) nsh[h * 8 + e] = t[e];
;                 load8f(nmrow + (nsub == 0 ? 1 : 4) * D + c8, t);
; #pragma unroll
;                 for (int e = 0; e < 8; ++e) nsc[h * 8 + e] = 1.f + t[e]; }
;         }
.Lrl_par_F:
	s_mov_b32 s65, s4
	s_mul_i32 s5, s25, 40
	s_add_i32 s5, s5, s4
	s_mul_i32 s5, s5, 0x6000
	s_mul_i32 s6, s72, 0x3000
	s_add_i32 s5, s5, s6
	s_add_u32 s6, s70, s5
	s_addc_u32 s7, s71, 0
	s_add_u32 s8, s6, 0x1000
	s_addc_u32 s9, s7, 0
	s_add_u32 s10, s6, 0x2000
	s_addc_u32 s11, s7, 0
	global_load_dwordx4 v[40:43], v6, s[6:7]
	global_load_dwordx4 v[44:47], v6, s[6:7] offset:16
	global_load_dwordx4 v[48:51], v6, s[6:7] offset:2048
	global_load_dwordx4 v[52:55], v6, s[6:7] offset:2064
	global_load_dwordx4 v[24:27], v6, s[8:9]
	global_load_dwordx4 v[28:31], v6, s[8:9] offset:16
	global_load_dwordx4 v[32:35], v6, s[8:9] offset:2048
	global_load_dwordx4 v[36:39], v6, s[8:9] offset:2064
	global_load_dwordx4 v[8:11], v6, s[10:11]
	global_load_dwordx4 v[12:15], v6, s[10:11] offset:16
	global_load_dwordx4 v[16:19], v6, s[10:11] offset:2048
	global_load_dwordx4 v[20:23], v6, s[10:11] offset:2064
	global_load_dwordx4 v[56:59], v6, s[80:81]
	global_load_dwordx4 v[60:63], v6, s[80:81] offset:16
	global_load_dwordx4 v[64:67], v6, s[80:81] offset:2048
	global_load_dwordx4 v[68:71], v6, s[80:81] offset:2064
	global_load_dwordx4 v[72:75], v6, s[82:83]
	global_load_dwordx4 v[76:79], v6, s[82:83] offset:16
	global_load_dwordx4 v[80:83], v6, s[82:83] offset:2048
	global_load_dwordx4 v[84:87], v6, s[82:83] offset:2064
	s_waitcnt vmcnt(0)
	v_pk_add_f32 v[8:9], v[8:9], 1.0 op_sel_hi:[1,0]
	v_pk_add_f32 v[10:11], v[10:11], 1.0 op_sel_hi:[1,0]
	v_pk_add_f32 v[12:13], v[12:13], 1.0 op_sel_hi:[1,0]
	v_pk_add_f32 v[14:15], v[14:15], 1.0 op_sel_hi:[1,0]
	v_pk_add_f32 v[16:17], v[16:17], 1.0 op_sel_hi:[1,0]
	v_pk_add_f32 v[18:19], v[18:19], 1.0 op_sel_hi:[1,0]
	v_pk_add_f32 v[20:21], v[20:21], 1.0 op_sel_hi:[1,0]
	v_pk_add_f32 v[22:23], v[22:23], 1.0 op_sel_hi:[1,0]
	v_pk_add_f32 v[24:25], v[24:25], 1.0 op_sel_hi:[1,0]
	v_pk_add_f32 v[26:27], v[26:27], 1.0 op_sel_hi:[1,0]
	v_pk_add_f32 v[28:29], v[28:29], 1.0 op_sel_hi:[1,0]
	v_pk_add_f32 v[30:31], v[30:31], 1.0 op_sel_hi:[1,0]
	v_pk_add_f32 v[32:33], v[32:33], 1.0 op_sel_hi:[1,0]
	v_pk_add_f32 v[34:35], v[34:35], 1.0 op_sel_hi:[1,0]
	v_pk_add_f32 v[36:37], v[36:37], 1.0 op_sel_hi:[1,0]
	v_pk_add_f32 v[38:39], v[38:39], 1.0 op_sel_hi:[1,0]
	v_rcp_f32_e32 v24, v24
	v_rcp_f32_e32 v25, v25
	v_rcp_f32_e32 v26, v26
	v_rcp_f32_e32 v27, v27
	v_rcp_f32_e32 v28, v28
	v_rcp_f32_e32 v29, v29
	v_rcp_f32_e32 v30, v30
	v_rcp_f32_e32 v31, v31
	v_rcp_f32_e32 v32, v32
	v_rcp_f32_e32 v33, v33
	v_rcp_f32_e32 v34, v34
	v_rcp_f32_e32 v35, v35
	v_rcp_f32_e32 v36, v36
	v_rcp_f32_e32 v37, v37
	v_rcp_f32_e32 v38, v38
	v_rcp_f32_e32 v39, v39
	v_pk_mul_f32 v[24:25], v[24:25], s[36:37] op_sel_hi:[1,0]
	v_pk_mul_f32 v[26:27], v[26:27], s[36:37] op_sel_hi:[1,0]
	v_pk_mul_f32 v[28:29], v[28:29], s[36:37] op_sel_hi:[1,0]
	v_pk_mul_f32 v[30:31], v[30:31], s[36:37] op_sel_hi:[1,0]
	v_pk_mul_f32 v[32:33], v[32:33], s[36:37] op_sel_hi:[1,0]
	v_pk_mul_f32 v[34:35], v[34:35], s[36:37] op_sel_hi:[1,0]
	v_pk_mul_f32 v[36:37], v[36:37], s[36:37] op_sel_hi:[1,0]
	v_pk_mul_f32 v[38:39], v[38:39], s[36:37] op_sel_hi:[1,0]
	v_pk_mul_f32 v[40:41], v[40:41], v[24:25] neg_lo:[1,0] neg_hi:[1,0]
	v_pk_mul_f32 v[42:43], v[42:43], v[26:27] neg_lo:[1,0] neg_hi:[1,0]
	v_pk_mul_f32 v[44:45], v[44:45], v[28:29] neg_lo:[1,0] neg_hi:[1,0]
	v_pk_mul_f32 v[46:47], v[46:47], v[30:31] neg_lo:[1,0] neg_hi:[1,0]
	v_pk_mul_f32 v[48:49], v[48:49], v[32:33] neg_lo:[1,0] neg_hi:[1,0]
	v_pk_mul_f32 v[50:51], v[50:51], v[34:35] neg_lo:[1,0] neg_hi:[1,0]
	v_pk_mul_f32 v[52:53], v[52:53], v[36:37] neg_lo:[1,0] neg_hi:[1,0]
	v_pk_mul_f32 v[54:55], v[54:55], v[38:39] neg_lo:[1,0] neg_hi:[1,0]
	s_nop 1
	s_cmp_eq_u32 s91, 0
	s_cbranch_scc1 .Lrl_F_okA
	s_branch .Lrl_F_okB
.Lrl_done:
	s_mov_b64 s[68:69], exec
	s_mov_b32 s83, 0x42b17218
